# speedup vs baseline: 1.0008x; 1.0008x over previous
.LBB0_370:
	v_ashrrev_i32_e32 v145, 31, v144
	v_lshl_add_u64 v[140:141], v[144:145], 4, s[10:11]
	s_mov_b64 s[8:9], -1
	s_and_b64 vcc, exec, s[6:7]
	s_cbranch_vccz .LBB0_432
	v_lshl_add_u64 v[142:143], v[144:145], 4, s[12:13]
	s_mov_b64 s[8:9], 0x1000
	v_mov_b64_e32 v[246:247], v[140:141]
	s_cmp_lt_u32 s81, 2
	s_cbranch_scc1 .Lgepi_0
	s_cmp_gt_u32 s81, 3
	s_cbranch_scc1 .Lgepi_2
	v_mov_b64_e32 v[248:249], v[142:143]
	v_mov_b64_e32 v[202:203], v[142:143]
	global_load_dwordx4 v[98:101], v[246:247], off
	v_lshl_add_u64 v[246:247], v[246:247], 0, s[8:9]
	global_load_dwordx4 v[102:105], v[246:247], off
	v_lshl_add_u64 v[246:247], v[246:247], 0, s[8:9]
	global_load_dwordx4 v[106:109], v[248:249], off
	v_lshl_add_u64 v[248:249], v[248:249], 0, s[8:9]
	global_load_dwordx4 v[110:113], v[248:249], off
	v_lshl_add_u64 v[248:249], v[248:249], 0, s[8:9]
	global_load_dwordx4 v[114:117], v[248:249], off
	v_lshl_add_u64 v[248:249], v[248:249], 0, s[8:9]
	global_load_dwordx4 v[118:121], v[248:249], off
	v_lshl_add_u64 v[248:249], v[248:249], 0, s[8:9]
	global_load_dwordx4 v[154:157], v[246:247], off
	v_lshl_add_u64 v[246:247], v[246:247], 0, s[8:9]
	global_load_dwordx4 v[158:161], v[246:247], off
	v_lshl_add_u64 v[246:247], v[246:247], 0, s[8:9]
	global_load_dwordx4 v[162:165], v[248:249], off
	v_lshl_add_u64 v[248:249], v[248:249], 0, s[8:9]
	global_load_dwordx4 v[166:169], v[248:249], off
	v_lshl_add_u64 v[248:249], v[248:249], 0, s[8:9]
	global_load_dwordx4 v[170:173], v[248:249], off
	v_lshl_add_u64 v[248:249], v[248:249], 0, s[8:9]
	global_load_dwordx4 v[174:177], v[248:249], off
	v_lshl_add_u64 v[248:249], v[248:249], 0, s[8:9]
	global_load_dwordx4 v[178:181], v[246:247], off
	v_lshl_add_u64 v[246:247], v[246:247], 0, s[8:9]
	global_load_dwordx4 v[182:185], v[246:247], off
	v_lshl_add_u64 v[246:247], v[246:247], 0, s[8:9]
	global_load_dwordx4 v[186:189], v[248:249], off
	v_lshl_add_u64 v[248:249], v[248:249], 0, s[8:9]
	global_load_dwordx4 v[190:193], v[248:249], off
	v_lshl_add_u64 v[248:249], v[248:249], 0, s[8:9]
	global_load_dwordx4 v[194:197], v[248:249], off
	v_lshl_add_u64 v[248:249], v[248:249], 0, s[8:9]
	global_load_dwordx4 v[198:201], v[248:249], off
	v_lshl_add_u64 v[248:249], v[248:249], 0, s[8:9]
	s_waitcnt vmcnt(12)
	v_mul_f32_e32 v230, 0xbfb8aa3b, v92
	v_mul_f32_e32 v231, 0xbfb8aa3b, v93
	v_mul_f32_e32 v232, 0xbfb8aa3b, v94
	v_mul_f32_e32 v233, 0xbfb8aa3b, v95
	v_mul_f32_e32 v234, 0xbfb8aa3b, v88
	v_mul_f32_e32 v235, 0xbfb8aa3b, v89
	v_mul_f32_e32 v236, 0xbfb8aa3b, v90
	v_mul_f32_e32 v237, 0xbfb8aa3b, v91
	v_exp_f32_e32 v230, v230
	v_exp_f32_e32 v231, v231
	v_exp_f32_e32 v232, v232
	v_exp_f32_e32 v233, v233
	v_exp_f32_e32 v234, v234
	v_exp_f32_e32 v235, v235
	v_exp_f32_e32 v236, v236
	v_exp_f32_e32 v237, v237
	v_add_f32_e32 v230, 1.0, v230
	v_add_f32_e32 v231, 1.0, v231
	v_add_f32_e32 v232, 1.0, v232
	v_add_f32_e32 v233, 1.0, v233
	v_add_f32_e32 v234, 1.0, v234
	v_add_f32_e32 v235, 1.0, v235
	v_add_f32_e32 v236, 1.0, v236
	v_add_f32_e32 v237, 1.0, v237
	v_rcp_f32_e32 v230, v230
	v_rcp_f32_e32 v231, v231
	v_rcp_f32_e32 v232, v232
	v_rcp_f32_e32 v233, v233
	v_rcp_f32_e32 v234, v234
	v_rcp_f32_e32 v235, v235
	v_rcp_f32_e32 v236, v236
	v_rcp_f32_e32 v237, v237
	v_lshlrev_b32_e32 v238, 16, v98
	v_and_b32_e32 v239, 0xffff0000, v98
	v_lshlrev_b32_e32 v240, 16, v99
	v_and_b32_e32 v241, 0xffff0000, v99
	v_lshlrev_b32_e32 v242, 16, v100
	v_and_b32_e32 v243, 0xffff0000, v100
	v_lshlrev_b32_e32 v244, 16, v101
	v_and_b32_e32 v245, 0xffff0000, v101
	v_pk_fma_f32 v[106:107], v[230:231], v[238:239], v[106:107]
	v_pk_fma_f32 v[108:109], v[232:233], v[240:241], v[108:109]
	v_pk_fma_f32 v[110:111], v[234:235], v[242:243], v[110:111]
	v_pk_fma_f32 v[112:113], v[236:237], v[244:245], v[112:113]
	v_mul_f32_e32 v230, 0xbfb8aa3b, v84
	v_mul_f32_e32 v231, 0xbfb8aa3b, v85
	v_mul_f32_e32 v232, 0xbfb8aa3b, v86
	v_mul_f32_e32 v233, 0xbfb8aa3b, v87
	v_mul_f32_e32 v234, 0xbfb8aa3b, v80
	v_mul_f32_e32 v235, 0xbfb8aa3b, v81
	v_mul_f32_e32 v236, 0xbfb8aa3b, v82
	v_mul_f32_e32 v237, 0xbfb8aa3b, v83
	v_exp_f32_e32 v230, v230
	v_exp_f32_e32 v231, v231
	v_exp_f32_e32 v232, v232
	v_exp_f32_e32 v233, v233
	v_exp_f32_e32 v234, v234
	v_exp_f32_e32 v235, v235
	v_exp_f32_e32 v236, v236
	v_exp_f32_e32 v237, v237
	v_add_f32_e32 v230, 1.0, v230
	v_add_f32_e32 v231, 1.0, v231
	v_add_f32_e32 v232, 1.0, v232
	v_add_f32_e32 v233, 1.0, v233
	v_add_f32_e32 v234, 1.0, v234
	v_add_f32_e32 v235, 1.0, v235
	v_add_f32_e32 v236, 1.0, v236
	v_add_f32_e32 v237, 1.0, v237
	v_rcp_f32_e32 v230, v230
	v_rcp_f32_e32 v231, v231
	v_rcp_f32_e32 v232, v232
	v_rcp_f32_e32 v233, v233
	v_rcp_f32_e32 v234, v234
	v_rcp_f32_e32 v235, v235
	v_rcp_f32_e32 v236, v236
	v_rcp_f32_e32 v237, v237
	v_lshlrev_b32_e32 v238, 16, v102
	v_and_b32_e32 v239, 0xffff0000, v102
	v_lshlrev_b32_e32 v240, 16, v103
	v_and_b32_e32 v241, 0xffff0000, v103
	v_lshlrev_b32_e32 v242, 16, v104
	v_and_b32_e32 v243, 0xffff0000, v104
	v_lshlrev_b32_e32 v244, 16, v105
	v_and_b32_e32 v245, 0xffff0000, v105
	v_pk_fma_f32 v[114:115], v[230:231], v[238:239], v[114:115]
	v_pk_fma_f32 v[116:117], v[232:233], v[240:241], v[116:117]
	v_pk_fma_f32 v[118:119], v[234:235], v[242:243], v[118:119]
	v_pk_fma_f32 v[120:121], v[236:237], v[244:245], v[120:121]
	global_store_dwordx4 v[202:203], v[106:109], off
	v_lshl_add_u64 v[202:203], v[202:203], 0, s[8:9]
	global_store_dwordx4 v[202:203], v[110:113], off
	v_lshl_add_u64 v[202:203], v[202:203], 0, s[8:9]
	global_store_dwordx4 v[202:203], v[114:117], off
	v_lshl_add_u64 v[202:203], v[202:203], 0, s[8:9]
	global_store_dwordx4 v[202:203], v[118:121], off
	v_lshl_add_u64 v[202:203], v[202:203], 0, s[8:9]
	global_load_dwordx4 v[98:101], v[246:247], off
	v_lshl_add_u64 v[246:247], v[246:247], 0, s[8:9]
	global_load_dwordx4 v[102:105], v[246:247], off
	v_lshl_add_u64 v[246:247], v[246:247], 0, s[8:9]
	global_load_dwordx4 v[106:109], v[248:249], off
	v_lshl_add_u64 v[248:249], v[248:249], 0, s[8:9]
	global_load_dwordx4 v[110:113], v[248:249], off
	v_lshl_add_u64 v[248:249], v[248:249], 0, s[8:9]
	global_load_dwordx4 v[114:117], v[248:249], off
	v_lshl_add_u64 v[248:249], v[248:249], 0, s[8:9]
	global_load_dwordx4 v[118:121], v[248:249], off
	v_lshl_add_u64 v[248:249], v[248:249], 0, s[8:9]
	s_waitcnt vmcnt(16)
	v_mul_f32_e32 v230, 0xbfb8aa3b, v76
	v_mul_f32_e32 v231, 0xbfb8aa3b, v77
	v_mul_f32_e32 v232, 0xbfb8aa3b, v78
	v_mul_f32_e32 v233, 0xbfb8aa3b, v79
	v_mul_f32_e32 v234, 0xbfb8aa3b, v72
	v_mul_f32_e32 v235, 0xbfb8aa3b, v73
	v_mul_f32_e32 v236, 0xbfb8aa3b, v74
	v_mul_f32_e32 v237, 0xbfb8aa3b, v75
	v_exp_f32_e32 v230, v230
	v_exp_f32_e32 v231, v231
	v_exp_f32_e32 v232, v232
	v_exp_f32_e32 v233, v233
	v_exp_f32_e32 v234, v234
	v_exp_f32_e32 v235, v235
	v_exp_f32_e32 v236, v236
	v_exp_f32_e32 v237, v237
	v_add_f32_e32 v230, 1.0, v230
	v_add_f32_e32 v231, 1.0, v231
	v_add_f32_e32 v232, 1.0, v232
	v_add_f32_e32 v233, 1.0, v233
	v_add_f32_e32 v234, 1.0, v234
	v_add_f32_e32 v235, 1.0, v235
	v_add_f32_e32 v236, 1.0, v236
	v_add_f32_e32 v237, 1.0, v237
	v_rcp_f32_e32 v230, v230
	v_rcp_f32_e32 v231, v231
	v_rcp_f32_e32 v232, v232
	v_rcp_f32_e32 v233, v233
	v_rcp_f32_e32 v234, v234
	v_rcp_f32_e32 v235, v235
	v_rcp_f32_e32 v236, v236
	v_rcp_f32_e32 v237, v237
	v_lshlrev_b32_e32 v238, 16, v154
	v_and_b32_e32 v239, 0xffff0000, v154
	v_lshlrev_b32_e32 v240, 16, v155
	v_and_b32_e32 v241, 0xffff0000, v155
	v_lshlrev_b32_e32 v242, 16, v156
	v_and_b32_e32 v243, 0xffff0000, v156
	v_lshlrev_b32_e32 v244, 16, v157
	v_and_b32_e32 v245, 0xffff0000, v157
	v_pk_fma_f32 v[162:163], v[230:231], v[238:239], v[162:163]
	v_pk_fma_f32 v[164:165], v[232:233], v[240:241], v[164:165]
	v_pk_fma_f32 v[166:167], v[234:235], v[242:243], v[166:167]
	v_pk_fma_f32 v[168:169], v[236:237], v[244:245], v[168:169]
	v_mul_f32_e32 v230, 0xbfb8aa3b, v68
	v_mul_f32_e32 v231, 0xbfb8aa3b, v69
	v_mul_f32_e32 v232, 0xbfb8aa3b, v70
	v_mul_f32_e32 v233, 0xbfb8aa3b, v71
	v_mul_f32_e32 v234, 0xbfb8aa3b, v64
	v_mul_f32_e32 v235, 0xbfb8aa3b, v65
	v_mul_f32_e32 v236, 0xbfb8aa3b, v66
	v_mul_f32_e32 v237, 0xbfb8aa3b, v67
	v_exp_f32_e32 v230, v230
	v_exp_f32_e32 v231, v231
	v_exp_f32_e32 v232, v232
	v_exp_f32_e32 v233, v233
	v_exp_f32_e32 v234, v234
	v_exp_f32_e32 v235, v235
	v_exp_f32_e32 v236, v236
	v_exp_f32_e32 v237, v237
	v_add_f32_e32 v230, 1.0, v230
	v_add_f32_e32 v231, 1.0, v231
	v_add_f32_e32 v232, 1.0, v232
	v_add_f32_e32 v233, 1.0, v233
	v_add_f32_e32 v234, 1.0, v234
	v_add_f32_e32 v235, 1.0, v235
	v_add_f32_e32 v236, 1.0, v236
	v_add_f32_e32 v237, 1.0, v237
	v_rcp_f32_e32 v230, v230
	v_rcp_f32_e32 v231, v231
	v_rcp_f32_e32 v232, v232
	v_rcp_f32_e32 v233, v233
	v_rcp_f32_e32 v234, v234
	v_rcp_f32_e32 v235, v235
	v_rcp_f32_e32 v236, v236
	v_rcp_f32_e32 v237, v237
	v_lshlrev_b32_e32 v238, 16, v158
	v_and_b32_e32 v239, 0xffff0000, v158
	v_lshlrev_b32_e32 v240, 16, v159
	v_and_b32_e32 v241, 0xffff0000, v159
	v_lshlrev_b32_e32 v242, 16, v160
	v_and_b32_e32 v243, 0xffff0000, v160
	v_lshlrev_b32_e32 v244, 16, v161
	v_and_b32_e32 v245, 0xffff0000, v161
	v_pk_fma_f32 v[170:171], v[230:231], v[238:239], v[170:171]
	v_pk_fma_f32 v[172:173], v[232:233], v[240:241], v[172:173]
	v_pk_fma_f32 v[174:175], v[234:235], v[242:243], v[174:175]
	v_pk_fma_f32 v[176:177], v[236:237], v[244:245], v[176:177]
	global_store_dwordx4 v[202:203], v[162:165], off
	v_lshl_add_u64 v[202:203], v[202:203], 0, s[8:9]
	global_store_dwordx4 v[202:203], v[166:169], off
	v_lshl_add_u64 v[202:203], v[202:203], 0, s[8:9]
	global_store_dwordx4 v[202:203], v[170:173], off
	v_lshl_add_u64 v[202:203], v[202:203], 0, s[8:9]
	global_store_dwordx4 v[202:203], v[174:177], off
	v_lshl_add_u64 v[202:203], v[202:203], 0, s[8:9]
	global_load_dwordx4 v[154:157], v[246:247], off
	v_lshl_add_u64 v[246:247], v[246:247], 0, s[8:9]
	global_load_dwordx4 v[158:161], v[246:247], off
	v_lshl_add_u64 v[246:247], v[246:247], 0, s[8:9]
	global_load_dwordx4 v[162:165], v[248:249], off
	v_lshl_add_u64 v[248:249], v[248:249], 0, s[8:9]
	global_load_dwordx4 v[166:169], v[248:249], off
	v_lshl_add_u64 v[248:249], v[248:249], 0, s[8:9]
	global_load_dwordx4 v[170:173], v[248:249], off
	v_lshl_add_u64 v[248:249], v[248:249], 0, s[8:9]
	global_load_dwordx4 v[174:177], v[248:249], off
	v_lshl_add_u64 v[248:249], v[248:249], 0, s[8:9]
	s_waitcnt vmcnt(20)
	v_mul_f32_e32 v230, 0xbfb8aa3b, v60
	v_mul_f32_e32 v231, 0xbfb8aa3b, v61
	v_mul_f32_e32 v232, 0xbfb8aa3b, v62
	v_mul_f32_e32 v233, 0xbfb8aa3b, v63
	v_mul_f32_e32 v234, 0xbfb8aa3b, v56
	v_mul_f32_e32 v235, 0xbfb8aa3b, v57
	v_mul_f32_e32 v236, 0xbfb8aa3b, v58
	v_mul_f32_e32 v237, 0xbfb8aa3b, v59
	v_exp_f32_e32 v230, v230
	v_exp_f32_e32 v231, v231
	v_exp_f32_e32 v232, v232
	v_exp_f32_e32 v233, v233
	v_exp_f32_e32 v234, v234
	v_exp_f32_e32 v235, v235
	v_exp_f32_e32 v236, v236
	v_exp_f32_e32 v237, v237
	v_add_f32_e32 v230, 1.0, v230
	v_add_f32_e32 v231, 1.0, v231
	v_add_f32_e32 v232, 1.0, v232
	v_add_f32_e32 v233, 1.0, v233
	v_add_f32_e32 v234, 1.0, v234
	v_add_f32_e32 v235, 1.0, v235
	v_add_f32_e32 v236, 1.0, v236
	v_add_f32_e32 v237, 1.0, v237
	v_rcp_f32_e32 v230, v230
	v_rcp_f32_e32 v231, v231
	v_rcp_f32_e32 v232, v232
	v_rcp_f32_e32 v233, v233
	v_rcp_f32_e32 v234, v234
	v_rcp_f32_e32 v235, v235
	v_rcp_f32_e32 v236, v236
	v_rcp_f32_e32 v237, v237
	v_lshlrev_b32_e32 v238, 16, v178
	v_and_b32_e32 v239, 0xffff0000, v178
	v_lshlrev_b32_e32 v240, 16, v179
	v_and_b32_e32 v241, 0xffff0000, v179
	v_lshlrev_b32_e32 v242, 16, v180
	v_and_b32_e32 v243, 0xffff0000, v180
	v_lshlrev_b32_e32 v244, 16, v181
	v_and_b32_e32 v245, 0xffff0000, v181
	v_pk_fma_f32 v[186:187], v[230:231], v[238:239], v[186:187]
	v_pk_fma_f32 v[188:189], v[232:233], v[240:241], v[188:189]
	v_pk_fma_f32 v[190:191], v[234:235], v[242:243], v[190:191]
	v_pk_fma_f32 v[192:193], v[236:237], v[244:245], v[192:193]
	v_mul_f32_e32 v230, 0xbfb8aa3b, v52
	v_mul_f32_e32 v231, 0xbfb8aa3b, v53
	v_mul_f32_e32 v232, 0xbfb8aa3b, v54
	v_mul_f32_e32 v233, 0xbfb8aa3b, v55
	v_mul_f32_e32 v234, 0xbfb8aa3b, v48
	v_mul_f32_e32 v235, 0xbfb8aa3b, v49
	v_mul_f32_e32 v236, 0xbfb8aa3b, v50
	v_mul_f32_e32 v237, 0xbfb8aa3b, v51
	v_exp_f32_e32 v230, v230
	v_exp_f32_e32 v231, v231
	v_exp_f32_e32 v232, v232
	v_exp_f32_e32 v233, v233
	v_exp_f32_e32 v234, v234
	v_exp_f32_e32 v235, v235
	v_exp_f32_e32 v236, v236
	v_exp_f32_e32 v237, v237
	v_add_f32_e32 v230, 1.0, v230
	v_add_f32_e32 v231, 1.0, v231
	v_add_f32_e32 v232, 1.0, v232
	v_add_f32_e32 v233, 1.0, v233
	v_add_f32_e32 v234, 1.0, v234
	v_add_f32_e32 v235, 1.0, v235
	v_add_f32_e32 v236, 1.0, v236
	v_add_f32_e32 v237, 1.0, v237
	v_rcp_f32_e32 v230, v230
	v_rcp_f32_e32 v231, v231
	v_rcp_f32_e32 v232, v232
	v_rcp_f32_e32 v233, v233
	v_rcp_f32_e32 v234, v234
	v_rcp_f32_e32 v235, v235
	v_rcp_f32_e32 v236, v236
	v_rcp_f32_e32 v237, v237
	v_lshlrev_b32_e32 v238, 16, v182
	v_and_b32_e32 v239, 0xffff0000, v182
	v_lshlrev_b32_e32 v240, 16, v183
	v_and_b32_e32 v241, 0xffff0000, v183
	v_lshlrev_b32_e32 v242, 16, v184
	v_and_b32_e32 v243, 0xffff0000, v184
	v_lshlrev_b32_e32 v244, 16, v185
	v_and_b32_e32 v245, 0xffff0000, v185
	v_pk_fma_f32 v[194:195], v[230:231], v[238:239], v[194:195]
	v_pk_fma_f32 v[196:197], v[232:233], v[240:241], v[196:197]
	v_pk_fma_f32 v[198:199], v[234:235], v[242:243], v[198:199]
	v_pk_fma_f32 v[200:201], v[236:237], v[244:245], v[200:201]
	global_store_dwordx4 v[202:203], v[186:189], off
	v_lshl_add_u64 v[202:203], v[202:203], 0, s[8:9]
	global_store_dwordx4 v[202:203], v[190:193], off
	v_lshl_add_u64 v[202:203], v[202:203], 0, s[8:9]
	global_store_dwordx4 v[202:203], v[194:197], off
	v_lshl_add_u64 v[202:203], v[202:203], 0, s[8:9]
	global_store_dwordx4 v[202:203], v[198:201], off
	v_lshl_add_u64 v[202:203], v[202:203], 0, s[8:9]
	global_load_dwordx4 v[178:181], v[246:247], off
	v_lshl_add_u64 v[246:247], v[246:247], 0, s[8:9]
	global_load_dwordx4 v[182:185], v[246:247], off
	v_lshl_add_u64 v[246:247], v[246:247], 0, s[8:9]
	global_load_dwordx4 v[186:189], v[248:249], off
	v_lshl_add_u64 v[248:249], v[248:249], 0, s[8:9]
	global_load_dwordx4 v[190:193], v[248:249], off
	v_lshl_add_u64 v[248:249], v[248:249], 0, s[8:9]
	global_load_dwordx4 v[194:197], v[248:249], off
	v_lshl_add_u64 v[248:249], v[248:249], 0, s[8:9]
	global_load_dwordx4 v[198:201], v[248:249], off
	v_lshl_add_u64 v[248:249], v[248:249], 0, s[8:9]
	s_waitcnt vmcnt(20)
	v_mul_f32_e32 v230, 0xbfb8aa3b, v44
	v_mul_f32_e32 v231, 0xbfb8aa3b, v45
	v_mul_f32_e32 v232, 0xbfb8aa3b, v46
	v_mul_f32_e32 v233, 0xbfb8aa3b, v47
	v_mul_f32_e32 v234, 0xbfb8aa3b, v40
	v_mul_f32_e32 v235, 0xbfb8aa3b, v41
	v_mul_f32_e32 v236, 0xbfb8aa3b, v42
	v_mul_f32_e32 v237, 0xbfb8aa3b, v43
	v_exp_f32_e32 v230, v230
	v_exp_f32_e32 v231, v231
	v_exp_f32_e32 v232, v232
	v_exp_f32_e32 v233, v233
	v_exp_f32_e32 v234, v234
	v_exp_f32_e32 v235, v235
	v_exp_f32_e32 v236, v236
	v_exp_f32_e32 v237, v237
	v_add_f32_e32 v230, 1.0, v230
	v_add_f32_e32 v231, 1.0, v231
	v_add_f32_e32 v232, 1.0, v232
	v_add_f32_e32 v233, 1.0, v233
	v_add_f32_e32 v234, 1.0, v234
	v_add_f32_e32 v235, 1.0, v235
	v_add_f32_e32 v236, 1.0, v236
	v_add_f32_e32 v237, 1.0, v237
	v_rcp_f32_e32 v230, v230
	v_rcp_f32_e32 v231, v231
	v_rcp_f32_e32 v232, v232
	v_rcp_f32_e32 v233, v233
	v_rcp_f32_e32 v234, v234
	v_rcp_f32_e32 v235, v235
	v_rcp_f32_e32 v236, v236
	v_rcp_f32_e32 v237, v237
	v_lshlrev_b32_e32 v238, 16, v98
	v_and_b32_e32 v239, 0xffff0000, v98
	v_lshlrev_b32_e32 v240, 16, v99
	v_and_b32_e32 v241, 0xffff0000, v99
	v_lshlrev_b32_e32 v242, 16, v100
	v_and_b32_e32 v243, 0xffff0000, v100
	v_lshlrev_b32_e32 v244, 16, v101
	v_and_b32_e32 v245, 0xffff0000, v101
	v_pk_fma_f32 v[106:107], v[230:231], v[238:239], v[106:107]
	v_pk_fma_f32 v[108:109], v[232:233], v[240:241], v[108:109]
	v_pk_fma_f32 v[110:111], v[234:235], v[242:243], v[110:111]
	v_pk_fma_f32 v[112:113], v[236:237], v[244:245], v[112:113]
	v_mul_f32_e32 v230, 0xbfb8aa3b, v36
	v_mul_f32_e32 v231, 0xbfb8aa3b, v37
	v_mul_f32_e32 v232, 0xbfb8aa3b, v38
	v_mul_f32_e32 v233, 0xbfb8aa3b, v39
	v_mul_f32_e32 v234, 0xbfb8aa3b, v32
	v_mul_f32_e32 v235, 0xbfb8aa3b, v33
	v_mul_f32_e32 v236, 0xbfb8aa3b, v34
	v_mul_f32_e32 v237, 0xbfb8aa3b, v35
	v_exp_f32_e32 v230, v230
	v_exp_f32_e32 v231, v231
	v_exp_f32_e32 v232, v232
	v_exp_f32_e32 v233, v233
	v_exp_f32_e32 v234, v234
	v_exp_f32_e32 v235, v235
	v_exp_f32_e32 v236, v236
	v_exp_f32_e32 v237, v237
	v_add_f32_e32 v230, 1.0, v230
	v_add_f32_e32 v231, 1.0, v231
	v_add_f32_e32 v232, 1.0, v232
	v_add_f32_e32 v233, 1.0, v233
	v_add_f32_e32 v234, 1.0, v234
	v_add_f32_e32 v235, 1.0, v235
	v_add_f32_e32 v236, 1.0, v236
	v_add_f32_e32 v237, 1.0, v237
	v_rcp_f32_e32 v230, v230
	v_rcp_f32_e32 v231, v231
	v_rcp_f32_e32 v232, v232
	v_rcp_f32_e32 v233, v233
	v_rcp_f32_e32 v234, v234
	v_rcp_f32_e32 v235, v235
	v_rcp_f32_e32 v236, v236
	v_rcp_f32_e32 v237, v237
	v_lshlrev_b32_e32 v238, 16, v102
	v_and_b32_e32 v239, 0xffff0000, v102
	v_lshlrev_b32_e32 v240, 16, v103
	v_and_b32_e32 v241, 0xffff0000, v103
	v_lshlrev_b32_e32 v242, 16, v104
	v_and_b32_e32 v243, 0xffff0000, v104
	v_lshlrev_b32_e32 v244, 16, v105
	v_and_b32_e32 v245, 0xffff0000, v105
	v_pk_fma_f32 v[114:115], v[230:231], v[238:239], v[114:115]
	v_pk_fma_f32 v[116:117], v[232:233], v[240:241], v[116:117]
	v_pk_fma_f32 v[118:119], v[234:235], v[242:243], v[118:119]
	v_pk_fma_f32 v[120:121], v[236:237], v[244:245], v[120:121]
	global_store_dwordx4 v[202:203], v[106:109], off
	v_lshl_add_u64 v[202:203], v[202:203], 0, s[8:9]
	global_store_dwordx4 v[202:203], v[110:113], off
	v_lshl_add_u64 v[202:203], v[202:203], 0, s[8:9]
	global_store_dwordx4 v[202:203], v[114:117], off
	v_lshl_add_u64 v[202:203], v[202:203], 0, s[8:9]
	global_store_dwordx4 v[202:203], v[118:121], off
	v_lshl_add_u64 v[202:203], v[202:203], 0, s[8:9]
	s_waitcnt vmcnt(14)
	v_mul_f32_e32 v230, 0xbfb8aa3b, v28
	v_mul_f32_e32 v231, 0xbfb8aa3b, v29
	v_mul_f32_e32 v232, 0xbfb8aa3b, v30
	v_mul_f32_e32 v233, 0xbfb8aa3b, v31
	v_mul_f32_e32 v234, 0xbfb8aa3b, v24
	v_mul_f32_e32 v235, 0xbfb8aa3b, v25
	v_mul_f32_e32 v236, 0xbfb8aa3b, v26
	v_mul_f32_e32 v237, 0xbfb8aa3b, v27
	v_exp_f32_e32 v230, v230
	v_exp_f32_e32 v231, v231
	v_exp_f32_e32 v232, v232
	v_exp_f32_e32 v233, v233
	v_exp_f32_e32 v234, v234
	v_exp_f32_e32 v235, v235
	v_exp_f32_e32 v236, v236
	v_exp_f32_e32 v237, v237
	v_add_f32_e32 v230, 1.0, v230
	v_add_f32_e32 v231, 1.0, v231
	v_add_f32_e32 v232, 1.0, v232
	v_add_f32_e32 v233, 1.0, v233
	v_add_f32_e32 v234, 1.0, v234
	v_add_f32_e32 v235, 1.0, v235
	v_add_f32_e32 v236, 1.0, v236
	v_add_f32_e32 v237, 1.0, v237
	v_rcp_f32_e32 v230, v230
	v_rcp_f32_e32 v231, v231
	v_rcp_f32_e32 v232, v232
	v_rcp_f32_e32 v233, v233
	v_rcp_f32_e32 v234, v234
	v_rcp_f32_e32 v235, v235
	v_rcp_f32_e32 v236, v236
	v_rcp_f32_e32 v237, v237
	v_lshlrev_b32_e32 v238, 16, v154
	v_and_b32_e32 v239, 0xffff0000, v154
	v_lshlrev_b32_e32 v240, 16, v155
	v_and_b32_e32 v241, 0xffff0000, v155
	v_lshlrev_b32_e32 v242, 16, v156
	v_and_b32_e32 v243, 0xffff0000, v156
	v_lshlrev_b32_e32 v244, 16, v157
	v_and_b32_e32 v245, 0xffff0000, v157
	v_pk_fma_f32 v[162:163], v[230:231], v[238:239], v[162:163]
	v_pk_fma_f32 v[164:165], v[232:233], v[240:241], v[164:165]
	v_pk_fma_f32 v[166:167], v[234:235], v[242:243], v[166:167]
	v_pk_fma_f32 v[168:169], v[236:237], v[244:245], v[168:169]
	v_mul_f32_e32 v230, 0xbfb8aa3b, v20
	v_mul_f32_e32 v231, 0xbfb8aa3b, v21
	v_mul_f32_e32 v232, 0xbfb8aa3b, v22
	v_mul_f32_e32 v233, 0xbfb8aa3b, v23
	v_mul_f32_e32 v234, 0xbfb8aa3b, v16
	v_mul_f32_e32 v235, 0xbfb8aa3b, v17
	v_mul_f32_e32 v236, 0xbfb8aa3b, v18
	v_mul_f32_e32 v237, 0xbfb8aa3b, v19
	v_exp_f32_e32 v230, v230
	v_exp_f32_e32 v231, v231
	v_exp_f32_e32 v232, v232
	v_exp_f32_e32 v233, v233
	v_exp_f32_e32 v234, v234
	v_exp_f32_e32 v235, v235
	v_exp_f32_e32 v236, v236
	v_exp_f32_e32 v237, v237
	v_add_f32_e32 v230, 1.0, v230
	v_add_f32_e32 v231, 1.0, v231
	v_add_f32_e32 v232, 1.0, v232
	v_add_f32_e32 v233, 1.0, v233
	v_add_f32_e32 v234, 1.0, v234
	v_add_f32_e32 v235, 1.0, v235
	v_add_f32_e32 v236, 1.0, v236
	v_add_f32_e32 v237, 1.0, v237
	v_rcp_f32_e32 v230, v230
	v_rcp_f32_e32 v231, v231
	v_rcp_f32_e32 v232, v232
	v_rcp_f32_e32 v233, v233
	v_rcp_f32_e32 v234, v234
	v_rcp_f32_e32 v235, v235
	v_rcp_f32_e32 v236, v236
	v_rcp_f32_e32 v237, v237
	v_lshlrev_b32_e32 v238, 16, v158
	v_and_b32_e32 v239, 0xffff0000, v158
	v_lshlrev_b32_e32 v240, 16, v159
	v_and_b32_e32 v241, 0xffff0000, v159
	v_lshlrev_b32_e32 v242, 16, v160
	v_and_b32_e32 v243, 0xffff0000, v160
	v_lshlrev_b32_e32 v244, 16, v161
	v_and_b32_e32 v245, 0xffff0000, v161
	v_pk_fma_f32 v[170:171], v[230:231], v[238:239], v[170:171]
	v_pk_fma_f32 v[172:173], v[232:233], v[240:241], v[172:173]
	v_pk_fma_f32 v[174:175], v[234:235], v[242:243], v[174:175]
	v_pk_fma_f32 v[176:177], v[236:237], v[244:245], v[176:177]
	global_store_dwordx4 v[202:203], v[162:165], off
	v_lshl_add_u64 v[202:203], v[202:203], 0, s[8:9]
	global_store_dwordx4 v[202:203], v[166:169], off
	v_lshl_add_u64 v[202:203], v[202:203], 0, s[8:9]
	global_store_dwordx4 v[202:203], v[170:173], off
	v_lshl_add_u64 v[202:203], v[202:203], 0, s[8:9]
	global_store_dwordx4 v[202:203], v[174:177], off
	v_lshl_add_u64 v[202:203], v[202:203], 0, s[8:9]
	s_waitcnt vmcnt(8)
	v_mul_f32_e32 v230, 0xbfb8aa3b, v12
	v_mul_f32_e32 v231, 0xbfb8aa3b, v13
	v_mul_f32_e32 v232, 0xbfb8aa3b, v14
	v_mul_f32_e32 v233, 0xbfb8aa3b, v15
	v_mul_f32_e32 v234, 0xbfb8aa3b, v8
	v_mul_f32_e32 v235, 0xbfb8aa3b, v9
	v_mul_f32_e32 v236, 0xbfb8aa3b, v10
	v_mul_f32_e32 v237, 0xbfb8aa3b, v11
	v_exp_f32_e32 v230, v230
	v_exp_f32_e32 v231, v231
	v_exp_f32_e32 v232, v232
	v_exp_f32_e32 v233, v233
	v_exp_f32_e32 v234, v234
	v_exp_f32_e32 v235, v235
	v_exp_f32_e32 v236, v236
	v_exp_f32_e32 v237, v237
	v_add_f32_e32 v230, 1.0, v230
	v_add_f32_e32 v231, 1.0, v231
	v_add_f32_e32 v232, 1.0, v232
	v_add_f32_e32 v233, 1.0, v233
	v_add_f32_e32 v234, 1.0, v234
	v_add_f32_e32 v235, 1.0, v235
	v_add_f32_e32 v236, 1.0, v236
	v_add_f32_e32 v237, 1.0, v237
	v_rcp_f32_e32 v230, v230
	v_rcp_f32_e32 v231, v231
	v_rcp_f32_e32 v232, v232
	v_rcp_f32_e32 v233, v233
	v_rcp_f32_e32 v234, v234
	v_rcp_f32_e32 v235, v235
	v_rcp_f32_e32 v236, v236
	v_rcp_f32_e32 v237, v237
	v_lshlrev_b32_e32 v238, 16, v178
	v_and_b32_e32 v239, 0xffff0000, v178
	v_lshlrev_b32_e32 v240, 16, v179
	v_and_b32_e32 v241, 0xffff0000, v179
	v_lshlrev_b32_e32 v242, 16, v180
	v_and_b32_e32 v243, 0xffff0000, v180
	v_lshlrev_b32_e32 v244, 16, v181
	v_and_b32_e32 v245, 0xffff0000, v181
	v_pk_fma_f32 v[186:187], v[230:231], v[238:239], v[186:187]
	v_pk_fma_f32 v[188:189], v[232:233], v[240:241], v[188:189]
	v_pk_fma_f32 v[190:191], v[234:235], v[242:243], v[190:191]
	v_pk_fma_f32 v[192:193], v[236:237], v[244:245], v[192:193]
	v_mul_f32_e32 v230, 0xbfb8aa3b, v4
	v_mul_f32_e32 v231, 0xbfb8aa3b, v5
	v_mul_f32_e32 v232, 0xbfb8aa3b, v6
	v_mul_f32_e32 v233, 0xbfb8aa3b, v7
	v_mul_f32_e32 v234, 0xbfb8aa3b, v0
	v_mul_f32_e32 v235, 0xbfb8aa3b, v1
	v_mul_f32_e32 v236, 0xbfb8aa3b, v2
	v_mul_f32_e32 v237, 0xbfb8aa3b, v3
	v_exp_f32_e32 v230, v230
	v_exp_f32_e32 v231, v231
	v_exp_f32_e32 v232, v232
	v_exp_f32_e32 v233, v233
	v_exp_f32_e32 v234, v234
	v_exp_f32_e32 v235, v235
	v_exp_f32_e32 v236, v236
	v_exp_f32_e32 v237, v237
	v_add_f32_e32 v230, 1.0, v230
	v_add_f32_e32 v231, 1.0, v231
	v_add_f32_e32 v232, 1.0, v232
	v_add_f32_e32 v233, 1.0, v233
	v_add_f32_e32 v234, 1.0, v234
	v_add_f32_e32 v235, 1.0, v235
	v_add_f32_e32 v236, 1.0, v236
	v_add_f32_e32 v237, 1.0, v237
	v_rcp_f32_e32 v230, v230
	v_rcp_f32_e32 v231, v231
	v_rcp_f32_e32 v232, v232
	v_rcp_f32_e32 v233, v233
	v_rcp_f32_e32 v234, v234
	v_rcp_f32_e32 v235, v235
	v_rcp_f32_e32 v236, v236
	v_rcp_f32_e32 v237, v237
	v_lshlrev_b32_e32 v238, 16, v182
	v_and_b32_e32 v239, 0xffff0000, v182
	v_lshlrev_b32_e32 v240, 16, v183
	v_and_b32_e32 v241, 0xffff0000, v183
	v_lshlrev_b32_e32 v242, 16, v184
	v_and_b32_e32 v243, 0xffff0000, v184
	v_lshlrev_b32_e32 v244, 16, v185
	v_and_b32_e32 v245, 0xffff0000, v185
	v_pk_fma_f32 v[194:195], v[230:231], v[238:239], v[194:195]
	v_pk_fma_f32 v[196:197], v[232:233], v[240:241], v[196:197]
	v_pk_fma_f32 v[198:199], v[234:235], v[242:243], v[198:199]
	v_pk_fma_f32 v[200:201], v[236:237], v[244:245], v[200:201]
	global_store_dwordx4 v[202:203], v[186:189], off
	v_lshl_add_u64 v[202:203], v[202:203], 0, s[8:9]
	global_store_dwordx4 v[202:203], v[190:193], off
	v_lshl_add_u64 v[202:203], v[202:203], 0, s[8:9]
	global_store_dwordx4 v[202:203], v[194:197], off
	v_lshl_add_u64 v[202:203], v[202:203], 0, s[8:9]
	global_store_dwordx4 v[202:203], v[198:201], off
	v_lshl_add_u64 v[202:203], v[202:203], 0, s[8:9]
	s_branch .LBB0_360
.Lgepi_0:
	v_mov_b64_e32 v[202:203], v[142:143]
	global_load_dwordx4 v[98:101], v[246:247], off
	v_lshl_add_u64 v[246:247], v[246:247], 0, s[8:9]
	global_load_dwordx4 v[102:105], v[246:247], off
	v_lshl_add_u64 v[246:247], v[246:247], 0, s[8:9]
	v_mov_b32_e32 v106, 0
	v_mov_b32_e32 v107, 0
	v_mov_b32_e32 v108, 0
	v_mov_b32_e32 v109, 0
	v_mov_b32_e32 v110, 0
	v_mov_b32_e32 v111, 0
	v_mov_b32_e32 v112, 0
	v_mov_b32_e32 v113, 0
	v_mov_b32_e32 v114, 0
	v_mov_b32_e32 v115, 0
	v_mov_b32_e32 v116, 0
	v_mov_b32_e32 v117, 0
	v_mov_b32_e32 v118, 0
	v_mov_b32_e32 v119, 0
	v_mov_b32_e32 v120, 0
	v_mov_b32_e32 v121, 0
	global_load_dwordx4 v[154:157], v[246:247], off
	v_lshl_add_u64 v[246:247], v[246:247], 0, s[8:9]
	global_load_dwordx4 v[158:161], v[246:247], off
	v_lshl_add_u64 v[246:247], v[246:247], 0, s[8:9]
	v_mov_b32_e32 v162, 0
	v_mov_b32_e32 v163, 0
	v_mov_b32_e32 v164, 0
	v_mov_b32_e32 v165, 0
	v_mov_b32_e32 v166, 0
	v_mov_b32_e32 v167, 0
	v_mov_b32_e32 v168, 0
	v_mov_b32_e32 v169, 0
	v_mov_b32_e32 v170, 0
	v_mov_b32_e32 v171, 0
	v_mov_b32_e32 v172, 0
	v_mov_b32_e32 v173, 0
	v_mov_b32_e32 v174, 0
	v_mov_b32_e32 v175, 0
	v_mov_b32_e32 v176, 0
	v_mov_b32_e32 v177, 0
	global_load_dwordx4 v[178:181], v[246:247], off
	v_lshl_add_u64 v[246:247], v[246:247], 0, s[8:9]
	global_load_dwordx4 v[182:185], v[246:247], off
	v_lshl_add_u64 v[246:247], v[246:247], 0, s[8:9]
	v_mov_b32_e32 v186, 0
	v_mov_b32_e32 v187, 0
	v_mov_b32_e32 v188, 0
	v_mov_b32_e32 v189, 0
	v_mov_b32_e32 v190, 0
	v_mov_b32_e32 v191, 0
	v_mov_b32_e32 v192, 0
	v_mov_b32_e32 v193, 0
	v_mov_b32_e32 v194, 0
	v_mov_b32_e32 v195, 0
	v_mov_b32_e32 v196, 0
	v_mov_b32_e32 v197, 0
	v_mov_b32_e32 v198, 0
	v_mov_b32_e32 v199, 0
	v_mov_b32_e32 v200, 0
	v_mov_b32_e32 v201, 0
	s_waitcnt vmcnt(4)
	v_mul_f32_e32 v230, 0xbfb8aa3b, v92
	v_mul_f32_e32 v231, 0xbfb8aa3b, v93
	v_mul_f32_e32 v232, 0xbfb8aa3b, v94
	v_mul_f32_e32 v233, 0xbfb8aa3b, v95
	v_mul_f32_e32 v234, 0xbfb8aa3b, v88
	v_mul_f32_e32 v235, 0xbfb8aa3b, v89
	v_mul_f32_e32 v236, 0xbfb8aa3b, v90
	v_mul_f32_e32 v237, 0xbfb8aa3b, v91
	v_exp_f32_e32 v230, v230
	v_exp_f32_e32 v231, v231
	v_exp_f32_e32 v232, v232
	v_exp_f32_e32 v233, v233
	v_exp_f32_e32 v234, v234
	v_exp_f32_e32 v235, v235
	v_exp_f32_e32 v236, v236
	v_exp_f32_e32 v237, v237
	v_add_f32_e32 v230, 1.0, v230
	v_add_f32_e32 v231, 1.0, v231
	v_add_f32_e32 v232, 1.0, v232
	v_add_f32_e32 v233, 1.0, v233
	v_add_f32_e32 v234, 1.0, v234
	v_add_f32_e32 v235, 1.0, v235
	v_add_f32_e32 v236, 1.0, v236
	v_add_f32_e32 v237, 1.0, v237
	v_rcp_f32_e32 v230, v230
	v_rcp_f32_e32 v231, v231
	v_rcp_f32_e32 v232, v232
	v_rcp_f32_e32 v233, v233
	v_rcp_f32_e32 v234, v234
	v_rcp_f32_e32 v235, v235
	v_rcp_f32_e32 v236, v236
	v_rcp_f32_e32 v237, v237
	v_lshlrev_b32_e32 v238, 16, v98
	v_and_b32_e32 v239, 0xffff0000, v98
	v_lshlrev_b32_e32 v240, 16, v99
	v_and_b32_e32 v241, 0xffff0000, v99
	v_lshlrev_b32_e32 v242, 16, v100
	v_and_b32_e32 v243, 0xffff0000, v100
	v_lshlrev_b32_e32 v244, 16, v101
	v_and_b32_e32 v245, 0xffff0000, v101
	v_pk_fma_f32 v[106:107], v[230:231], v[238:239], v[106:107]
	v_pk_fma_f32 v[108:109], v[232:233], v[240:241], v[108:109]
	v_pk_fma_f32 v[110:111], v[234:235], v[242:243], v[110:111]
	v_pk_fma_f32 v[112:113], v[236:237], v[244:245], v[112:113]
	v_mul_f32_e32 v230, 0xbfb8aa3b, v84
	v_mul_f32_e32 v231, 0xbfb8aa3b, v85
	v_mul_f32_e32 v232, 0xbfb8aa3b, v86
	v_mul_f32_e32 v233, 0xbfb8aa3b, v87
	v_mul_f32_e32 v234, 0xbfb8aa3b, v80
	v_mul_f32_e32 v235, 0xbfb8aa3b, v81
	v_mul_f32_e32 v236, 0xbfb8aa3b, v82
	v_mul_f32_e32 v237, 0xbfb8aa3b, v83
	v_exp_f32_e32 v230, v230
	v_exp_f32_e32 v231, v231
	v_exp_f32_e32 v232, v232
	v_exp_f32_e32 v233, v233
	v_exp_f32_e32 v234, v234
	v_exp_f32_e32 v235, v235
	v_exp_f32_e32 v236, v236
	v_exp_f32_e32 v237, v237
	v_add_f32_e32 v230, 1.0, v230
	v_add_f32_e32 v231, 1.0, v231
	v_add_f32_e32 v232, 1.0, v232
	v_add_f32_e32 v233, 1.0, v233
	v_add_f32_e32 v234, 1.0, v234
	v_add_f32_e32 v235, 1.0, v235
	v_add_f32_e32 v236, 1.0, v236
	v_add_f32_e32 v237, 1.0, v237
	v_rcp_f32_e32 v230, v230
	v_rcp_f32_e32 v231, v231
	v_rcp_f32_e32 v232, v232
	v_rcp_f32_e32 v233, v233
	v_rcp_f32_e32 v234, v234
	v_rcp_f32_e32 v235, v235
	v_rcp_f32_e32 v236, v236
	v_rcp_f32_e32 v237, v237
	v_lshlrev_b32_e32 v238, 16, v102
	v_and_b32_e32 v239, 0xffff0000, v102
	v_lshlrev_b32_e32 v240, 16, v103
	v_and_b32_e32 v241, 0xffff0000, v103
	v_lshlrev_b32_e32 v242, 16, v104
	v_and_b32_e32 v243, 0xffff0000, v104
	v_lshlrev_b32_e32 v244, 16, v105
	v_and_b32_e32 v245, 0xffff0000, v105
	v_pk_fma_f32 v[114:115], v[230:231], v[238:239], v[114:115]
	v_pk_fma_f32 v[116:117], v[232:233], v[240:241], v[116:117]
	v_pk_fma_f32 v[118:119], v[234:235], v[242:243], v[118:119]
	v_pk_fma_f32 v[120:121], v[236:237], v[244:245], v[120:121]
	global_store_dwordx4 v[202:203], v[106:109], off
	v_lshl_add_u64 v[202:203], v[202:203], 0, s[8:9]
	global_store_dwordx4 v[202:203], v[110:113], off
	v_lshl_add_u64 v[202:203], v[202:203], 0, s[8:9]
	global_store_dwordx4 v[202:203], v[114:117], off
	v_lshl_add_u64 v[202:203], v[202:203], 0, s[8:9]
	global_store_dwordx4 v[202:203], v[118:121], off
	v_lshl_add_u64 v[202:203], v[202:203], 0, s[8:9]
	global_load_dwordx4 v[98:101], v[246:247], off
	v_lshl_add_u64 v[246:247], v[246:247], 0, s[8:9]
	global_load_dwordx4 v[102:105], v[246:247], off
	v_lshl_add_u64 v[246:247], v[246:247], 0, s[8:9]
	v_mov_b32_e32 v106, 0
	v_mov_b32_e32 v107, 0
	v_mov_b32_e32 v108, 0
	v_mov_b32_e32 v109, 0
	v_mov_b32_e32 v110, 0
	v_mov_b32_e32 v111, 0
	v_mov_b32_e32 v112, 0
	v_mov_b32_e32 v113, 0
	v_mov_b32_e32 v114, 0
	v_mov_b32_e32 v115, 0
	v_mov_b32_e32 v116, 0
	v_mov_b32_e32 v117, 0
	v_mov_b32_e32 v118, 0
	v_mov_b32_e32 v119, 0
	v_mov_b32_e32 v120, 0
	v_mov_b32_e32 v121, 0
	s_waitcnt vmcnt(8)
	v_mul_f32_e32 v230, 0xbfb8aa3b, v76
	v_mul_f32_e32 v231, 0xbfb8aa3b, v77
	v_mul_f32_e32 v232, 0xbfb8aa3b, v78
	v_mul_f32_e32 v233, 0xbfb8aa3b, v79
	v_mul_f32_e32 v234, 0xbfb8aa3b, v72
	v_mul_f32_e32 v235, 0xbfb8aa3b, v73
	v_mul_f32_e32 v236, 0xbfb8aa3b, v74
	v_mul_f32_e32 v237, 0xbfb8aa3b, v75
	v_exp_f32_e32 v230, v230
	v_exp_f32_e32 v231, v231
	v_exp_f32_e32 v232, v232
	v_exp_f32_e32 v233, v233
	v_exp_f32_e32 v234, v234
	v_exp_f32_e32 v235, v235
	v_exp_f32_e32 v236, v236
	v_exp_f32_e32 v237, v237
	v_add_f32_e32 v230, 1.0, v230
	v_add_f32_e32 v231, 1.0, v231
	v_add_f32_e32 v232, 1.0, v232
	v_add_f32_e32 v233, 1.0, v233
	v_add_f32_e32 v234, 1.0, v234
	v_add_f32_e32 v235, 1.0, v235
	v_add_f32_e32 v236, 1.0, v236
	v_add_f32_e32 v237, 1.0, v237
	v_rcp_f32_e32 v230, v230
	v_rcp_f32_e32 v231, v231
	v_rcp_f32_e32 v232, v232
	v_rcp_f32_e32 v233, v233
	v_rcp_f32_e32 v234, v234
	v_rcp_f32_e32 v235, v235
	v_rcp_f32_e32 v236, v236
	v_rcp_f32_e32 v237, v237
	v_lshlrev_b32_e32 v238, 16, v154
	v_and_b32_e32 v239, 0xffff0000, v154
	v_lshlrev_b32_e32 v240, 16, v155
	v_and_b32_e32 v241, 0xffff0000, v155
	v_lshlrev_b32_e32 v242, 16, v156
	v_and_b32_e32 v243, 0xffff0000, v156
	v_lshlrev_b32_e32 v244, 16, v157
	v_and_b32_e32 v245, 0xffff0000, v157
	v_pk_fma_f32 v[162:163], v[230:231], v[238:239], v[162:163]
	v_pk_fma_f32 v[164:165], v[232:233], v[240:241], v[164:165]
	v_pk_fma_f32 v[166:167], v[234:235], v[242:243], v[166:167]
	v_pk_fma_f32 v[168:169], v[236:237], v[244:245], v[168:169]
	v_mul_f32_e32 v230, 0xbfb8aa3b, v68
	v_mul_f32_e32 v231, 0xbfb8aa3b, v69
	v_mul_f32_e32 v232, 0xbfb8aa3b, v70
	v_mul_f32_e32 v233, 0xbfb8aa3b, v71
	v_mul_f32_e32 v234, 0xbfb8aa3b, v64
	v_mul_f32_e32 v235, 0xbfb8aa3b, v65
	v_mul_f32_e32 v236, 0xbfb8aa3b, v66
	v_mul_f32_e32 v237, 0xbfb8aa3b, v67
	v_exp_f32_e32 v230, v230
	v_exp_f32_e32 v231, v231
	v_exp_f32_e32 v232, v232
	v_exp_f32_e32 v233, v233
	v_exp_f32_e32 v234, v234
	v_exp_f32_e32 v235, v235
	v_exp_f32_e32 v236, v236
	v_exp_f32_e32 v237, v237
	v_add_f32_e32 v230, 1.0, v230
	v_add_f32_e32 v231, 1.0, v231
	v_add_f32_e32 v232, 1.0, v232
	v_add_f32_e32 v233, 1.0, v233
	v_add_f32_e32 v234, 1.0, v234
	v_add_f32_e32 v235, 1.0, v235
	v_add_f32_e32 v236, 1.0, v236
	v_add_f32_e32 v237, 1.0, v237
	v_rcp_f32_e32 v230, v230
	v_rcp_f32_e32 v231, v231
	v_rcp_f32_e32 v232, v232
	v_rcp_f32_e32 v233, v233
	v_rcp_f32_e32 v234, v234
	v_rcp_f32_e32 v235, v235
	v_rcp_f32_e32 v236, v236
	v_rcp_f32_e32 v237, v237
	v_lshlrev_b32_e32 v238, 16, v158
	v_and_b32_e32 v239, 0xffff0000, v158
	v_lshlrev_b32_e32 v240, 16, v159
	v_and_b32_e32 v241, 0xffff0000, v159
	v_lshlrev_b32_e32 v242, 16, v160
	v_and_b32_e32 v243, 0xffff0000, v160
	v_lshlrev_b32_e32 v244, 16, v161
	v_and_b32_e32 v245, 0xffff0000, v161
	v_pk_fma_f32 v[170:171], v[230:231], v[238:239], v[170:171]
	v_pk_fma_f32 v[172:173], v[232:233], v[240:241], v[172:173]
	v_pk_fma_f32 v[174:175], v[234:235], v[242:243], v[174:175]
	v_pk_fma_f32 v[176:177], v[236:237], v[244:245], v[176:177]
	global_store_dwordx4 v[202:203], v[162:165], off
	v_lshl_add_u64 v[202:203], v[202:203], 0, s[8:9]
	global_store_dwordx4 v[202:203], v[166:169], off
	v_lshl_add_u64 v[202:203], v[202:203], 0, s[8:9]
	global_store_dwordx4 v[202:203], v[170:173], off
	v_lshl_add_u64 v[202:203], v[202:203], 0, s[8:9]
	global_store_dwordx4 v[202:203], v[174:177], off
	v_lshl_add_u64 v[202:203], v[202:203], 0, s[8:9]
	global_load_dwordx4 v[154:157], v[246:247], off
	v_lshl_add_u64 v[246:247], v[246:247], 0, s[8:9]
	global_load_dwordx4 v[158:161], v[246:247], off
	v_lshl_add_u64 v[246:247], v[246:247], 0, s[8:9]
	v_mov_b32_e32 v162, 0
	v_mov_b32_e32 v163, 0
	v_mov_b32_e32 v164, 0
	v_mov_b32_e32 v165, 0
	v_mov_b32_e32 v166, 0
	v_mov_b32_e32 v167, 0
	v_mov_b32_e32 v168, 0
	v_mov_b32_e32 v169, 0
	v_mov_b32_e32 v170, 0
	v_mov_b32_e32 v171, 0
	v_mov_b32_e32 v172, 0
	v_mov_b32_e32 v173, 0
	v_mov_b32_e32 v174, 0
	v_mov_b32_e32 v175, 0
	v_mov_b32_e32 v176, 0
	v_mov_b32_e32 v177, 0
	s_waitcnt vmcnt(12)
	v_mul_f32_e32 v230, 0xbfb8aa3b, v60
	v_mul_f32_e32 v231, 0xbfb8aa3b, v61
	v_mul_f32_e32 v232, 0xbfb8aa3b, v62
	v_mul_f32_e32 v233, 0xbfb8aa3b, v63
	v_mul_f32_e32 v234, 0xbfb8aa3b, v56
	v_mul_f32_e32 v235, 0xbfb8aa3b, v57
	v_mul_f32_e32 v236, 0xbfb8aa3b, v58
	v_mul_f32_e32 v237, 0xbfb8aa3b, v59
	v_exp_f32_e32 v230, v230
	v_exp_f32_e32 v231, v231
	v_exp_f32_e32 v232, v232
	v_exp_f32_e32 v233, v233
	v_exp_f32_e32 v234, v234
	v_exp_f32_e32 v235, v235
	v_exp_f32_e32 v236, v236
	v_exp_f32_e32 v237, v237
	v_add_f32_e32 v230, 1.0, v230
	v_add_f32_e32 v231, 1.0, v231
	v_add_f32_e32 v232, 1.0, v232
	v_add_f32_e32 v233, 1.0, v233
	v_add_f32_e32 v234, 1.0, v234
	v_add_f32_e32 v235, 1.0, v235
	v_add_f32_e32 v236, 1.0, v236
	v_add_f32_e32 v237, 1.0, v237
	v_rcp_f32_e32 v230, v230
	v_rcp_f32_e32 v231, v231
	v_rcp_f32_e32 v232, v232
	v_rcp_f32_e32 v233, v233
	v_rcp_f32_e32 v234, v234
	v_rcp_f32_e32 v235, v235
	v_rcp_f32_e32 v236, v236
	v_rcp_f32_e32 v237, v237
	v_lshlrev_b32_e32 v238, 16, v178
	v_and_b32_e32 v239, 0xffff0000, v178
	v_lshlrev_b32_e32 v240, 16, v179
	v_and_b32_e32 v241, 0xffff0000, v179
	v_lshlrev_b32_e32 v242, 16, v180
	v_and_b32_e32 v243, 0xffff0000, v180
	v_lshlrev_b32_e32 v244, 16, v181
	v_and_b32_e32 v245, 0xffff0000, v181
	v_pk_fma_f32 v[186:187], v[230:231], v[238:239], v[186:187]
	v_pk_fma_f32 v[188:189], v[232:233], v[240:241], v[188:189]
	v_pk_fma_f32 v[190:191], v[234:235], v[242:243], v[190:191]
	v_pk_fma_f32 v[192:193], v[236:237], v[244:245], v[192:193]
	v_mul_f32_e32 v230, 0xbfb8aa3b, v52
	v_mul_f32_e32 v231, 0xbfb8aa3b, v53
	v_mul_f32_e32 v232, 0xbfb8aa3b, v54
	v_mul_f32_e32 v233, 0xbfb8aa3b, v55
	v_mul_f32_e32 v234, 0xbfb8aa3b, v48
	v_mul_f32_e32 v235, 0xbfb8aa3b, v49
	v_mul_f32_e32 v236, 0xbfb8aa3b, v50
	v_mul_f32_e32 v237, 0xbfb8aa3b, v51
	v_exp_f32_e32 v230, v230
	v_exp_f32_e32 v231, v231
	v_exp_f32_e32 v232, v232
	v_exp_f32_e32 v233, v233
	v_exp_f32_e32 v234, v234
	v_exp_f32_e32 v235, v235
	v_exp_f32_e32 v236, v236
	v_exp_f32_e32 v237, v237
	v_add_f32_e32 v230, 1.0, v230
	v_add_f32_e32 v231, 1.0, v231
	v_add_f32_e32 v232, 1.0, v232
	v_add_f32_e32 v233, 1.0, v233
	v_add_f32_e32 v234, 1.0, v234
	v_add_f32_e32 v235, 1.0, v235
	v_add_f32_e32 v236, 1.0, v236
	v_add_f32_e32 v237, 1.0, v237
	v_rcp_f32_e32 v230, v230
	v_rcp_f32_e32 v231, v231
	v_rcp_f32_e32 v232, v232
	v_rcp_f32_e32 v233, v233
	v_rcp_f32_e32 v234, v234
	v_rcp_f32_e32 v235, v235
	v_rcp_f32_e32 v236, v236
	v_rcp_f32_e32 v237, v237
	v_lshlrev_b32_e32 v238, 16, v182
	v_and_b32_e32 v239, 0xffff0000, v182
	v_lshlrev_b32_e32 v240, 16, v183
	v_and_b32_e32 v241, 0xffff0000, v183
	v_lshlrev_b32_e32 v242, 16, v184
	v_and_b32_e32 v243, 0xffff0000, v184
	v_lshlrev_b32_e32 v244, 16, v185
	v_and_b32_e32 v245, 0xffff0000, v185
	v_pk_fma_f32 v[194:195], v[230:231], v[238:239], v[194:195]
	v_pk_fma_f32 v[196:197], v[232:233], v[240:241], v[196:197]
	v_pk_fma_f32 v[198:199], v[234:235], v[242:243], v[198:199]
	v_pk_fma_f32 v[200:201], v[236:237], v[244:245], v[200:201]
	global_store_dwordx4 v[202:203], v[186:189], off
	v_lshl_add_u64 v[202:203], v[202:203], 0, s[8:9]
	global_store_dwordx4 v[202:203], v[190:193], off
	v_lshl_add_u64 v[202:203], v[202:203], 0, s[8:9]
	global_store_dwordx4 v[202:203], v[194:197], off
	v_lshl_add_u64 v[202:203], v[202:203], 0, s[8:9]
	global_store_dwordx4 v[202:203], v[198:201], off
	v_lshl_add_u64 v[202:203], v[202:203], 0, s[8:9]
	global_load_dwordx4 v[178:181], v[246:247], off
	v_lshl_add_u64 v[246:247], v[246:247], 0, s[8:9]
	global_load_dwordx4 v[182:185], v[246:247], off
	v_lshl_add_u64 v[246:247], v[246:247], 0, s[8:9]
	v_mov_b32_e32 v186, 0
	v_mov_b32_e32 v187, 0
	v_mov_b32_e32 v188, 0
	v_mov_b32_e32 v189, 0
	v_mov_b32_e32 v190, 0
	v_mov_b32_e32 v191, 0
	v_mov_b32_e32 v192, 0
	v_mov_b32_e32 v193, 0
	v_mov_b32_e32 v194, 0
	v_mov_b32_e32 v195, 0
	v_mov_b32_e32 v196, 0
	v_mov_b32_e32 v197, 0
	v_mov_b32_e32 v198, 0
	v_mov_b32_e32 v199, 0
	v_mov_b32_e32 v200, 0
	v_mov_b32_e32 v201, 0
	s_waitcnt vmcnt(12)
	v_mul_f32_e32 v230, 0xbfb8aa3b, v44
	v_mul_f32_e32 v231, 0xbfb8aa3b, v45
	v_mul_f32_e32 v232, 0xbfb8aa3b, v46
	v_mul_f32_e32 v233, 0xbfb8aa3b, v47
	v_mul_f32_e32 v234, 0xbfb8aa3b, v40
	v_mul_f32_e32 v235, 0xbfb8aa3b, v41
	v_mul_f32_e32 v236, 0xbfb8aa3b, v42
	v_mul_f32_e32 v237, 0xbfb8aa3b, v43
	v_exp_f32_e32 v230, v230
	v_exp_f32_e32 v231, v231
	v_exp_f32_e32 v232, v232
	v_exp_f32_e32 v233, v233
	v_exp_f32_e32 v234, v234
	v_exp_f32_e32 v235, v235
	v_exp_f32_e32 v236, v236
	v_exp_f32_e32 v237, v237
	v_add_f32_e32 v230, 1.0, v230
	v_add_f32_e32 v231, 1.0, v231
	v_add_f32_e32 v232, 1.0, v232
	v_add_f32_e32 v233, 1.0, v233
	v_add_f32_e32 v234, 1.0, v234
	v_add_f32_e32 v235, 1.0, v235
	v_add_f32_e32 v236, 1.0, v236
	v_add_f32_e32 v237, 1.0, v237
	v_rcp_f32_e32 v230, v230
	v_rcp_f32_e32 v231, v231
	v_rcp_f32_e32 v232, v232
	v_rcp_f32_e32 v233, v233
	v_rcp_f32_e32 v234, v234
	v_rcp_f32_e32 v235, v235
	v_rcp_f32_e32 v236, v236
	v_rcp_f32_e32 v237, v237
	v_lshlrev_b32_e32 v238, 16, v98
	v_and_b32_e32 v239, 0xffff0000, v98
	v_lshlrev_b32_e32 v240, 16, v99
	v_and_b32_e32 v241, 0xffff0000, v99
	v_lshlrev_b32_e32 v242, 16, v100
	v_and_b32_e32 v243, 0xffff0000, v100
	v_lshlrev_b32_e32 v244, 16, v101
	v_and_b32_e32 v245, 0xffff0000, v101
	v_pk_fma_f32 v[106:107], v[230:231], v[238:239], v[106:107]
	v_pk_fma_f32 v[108:109], v[232:233], v[240:241], v[108:109]
	v_pk_fma_f32 v[110:111], v[234:235], v[242:243], v[110:111]
	v_pk_fma_f32 v[112:113], v[236:237], v[244:245], v[112:113]
	v_mul_f32_e32 v230, 0xbfb8aa3b, v36
	v_mul_f32_e32 v231, 0xbfb8aa3b, v37
	v_mul_f32_e32 v232, 0xbfb8aa3b, v38
	v_mul_f32_e32 v233, 0xbfb8aa3b, v39
	v_mul_f32_e32 v234, 0xbfb8aa3b, v32
	v_mul_f32_e32 v235, 0xbfb8aa3b, v33
	v_mul_f32_e32 v236, 0xbfb8aa3b, v34
	v_mul_f32_e32 v237, 0xbfb8aa3b, v35
	v_exp_f32_e32 v230, v230
	v_exp_f32_e32 v231, v231
	v_exp_f32_e32 v232, v232
	v_exp_f32_e32 v233, v233
	v_exp_f32_e32 v234, v234
	v_exp_f32_e32 v235, v235
	v_exp_f32_e32 v236, v236
	v_exp_f32_e32 v237, v237
	v_add_f32_e32 v230, 1.0, v230
	v_add_f32_e32 v231, 1.0, v231
	v_add_f32_e32 v232, 1.0, v232
	v_add_f32_e32 v233, 1.0, v233
	v_add_f32_e32 v234, 1.0, v234
	v_add_f32_e32 v235, 1.0, v235
	v_add_f32_e32 v236, 1.0, v236
	v_add_f32_e32 v237, 1.0, v237
	v_rcp_f32_e32 v230, v230
	v_rcp_f32_e32 v231, v231
	v_rcp_f32_e32 v232, v232
	v_rcp_f32_e32 v233, v233
	v_rcp_f32_e32 v234, v234
	v_rcp_f32_e32 v235, v235
	v_rcp_f32_e32 v236, v236
	v_rcp_f32_e32 v237, v237
	v_lshlrev_b32_e32 v238, 16, v102
	v_and_b32_e32 v239, 0xffff0000, v102
	v_lshlrev_b32_e32 v240, 16, v103
	v_and_b32_e32 v241, 0xffff0000, v103
	v_lshlrev_b32_e32 v242, 16, v104
	v_and_b32_e32 v243, 0xffff0000, v104
	v_lshlrev_b32_e32 v244, 16, v105
	v_and_b32_e32 v245, 0xffff0000, v105
	v_pk_fma_f32 v[114:115], v[230:231], v[238:239], v[114:115]
	v_pk_fma_f32 v[116:117], v[232:233], v[240:241], v[116:117]
	v_pk_fma_f32 v[118:119], v[234:235], v[242:243], v[118:119]
	v_pk_fma_f32 v[120:121], v[236:237], v[244:245], v[120:121]
	global_store_dwordx4 v[202:203], v[106:109], off
	v_lshl_add_u64 v[202:203], v[202:203], 0, s[8:9]
	global_store_dwordx4 v[202:203], v[110:113], off
	v_lshl_add_u64 v[202:203], v[202:203], 0, s[8:9]
	global_store_dwordx4 v[202:203], v[114:117], off
	v_lshl_add_u64 v[202:203], v[202:203], 0, s[8:9]
	global_store_dwordx4 v[202:203], v[118:121], off
	v_lshl_add_u64 v[202:203], v[202:203], 0, s[8:9]
	s_waitcnt vmcnt(10)
	v_mul_f32_e32 v230, 0xbfb8aa3b, v28
	v_mul_f32_e32 v231, 0xbfb8aa3b, v29
	v_mul_f32_e32 v232, 0xbfb8aa3b, v30
	v_mul_f32_e32 v233, 0xbfb8aa3b, v31
	v_mul_f32_e32 v234, 0xbfb8aa3b, v24
	v_mul_f32_e32 v235, 0xbfb8aa3b, v25
	v_mul_f32_e32 v236, 0xbfb8aa3b, v26
	v_mul_f32_e32 v237, 0xbfb8aa3b, v27
	v_exp_f32_e32 v230, v230
	v_exp_f32_e32 v231, v231
	v_exp_f32_e32 v232, v232
	v_exp_f32_e32 v233, v233
	v_exp_f32_e32 v234, v234
	v_exp_f32_e32 v235, v235
	v_exp_f32_e32 v236, v236
	v_exp_f32_e32 v237, v237
	v_add_f32_e32 v230, 1.0, v230
	v_add_f32_e32 v231, 1.0, v231
	v_add_f32_e32 v232, 1.0, v232
	v_add_f32_e32 v233, 1.0, v233
	v_add_f32_e32 v234, 1.0, v234
	v_add_f32_e32 v235, 1.0, v235
	v_add_f32_e32 v236, 1.0, v236
	v_add_f32_e32 v237, 1.0, v237
	v_rcp_f32_e32 v230, v230
	v_rcp_f32_e32 v231, v231
	v_rcp_f32_e32 v232, v232
	v_rcp_f32_e32 v233, v233
	v_rcp_f32_e32 v234, v234
	v_rcp_f32_e32 v235, v235
	v_rcp_f32_e32 v236, v236
	v_rcp_f32_e32 v237, v237
	v_lshlrev_b32_e32 v238, 16, v154
	v_and_b32_e32 v239, 0xffff0000, v154
	v_lshlrev_b32_e32 v240, 16, v155
	v_and_b32_e32 v241, 0xffff0000, v155
	v_lshlrev_b32_e32 v242, 16, v156
	v_and_b32_e32 v243, 0xffff0000, v156
	v_lshlrev_b32_e32 v244, 16, v157
	v_and_b32_e32 v245, 0xffff0000, v157
	v_pk_fma_f32 v[162:163], v[230:231], v[238:239], v[162:163]
	v_pk_fma_f32 v[164:165], v[232:233], v[240:241], v[164:165]
	v_pk_fma_f32 v[166:167], v[234:235], v[242:243], v[166:167]
	v_pk_fma_f32 v[168:169], v[236:237], v[244:245], v[168:169]
	v_mul_f32_e32 v230, 0xbfb8aa3b, v20
	v_mul_f32_e32 v231, 0xbfb8aa3b, v21
	v_mul_f32_e32 v232, 0xbfb8aa3b, v22
	v_mul_f32_e32 v233, 0xbfb8aa3b, v23
	v_mul_f32_e32 v234, 0xbfb8aa3b, v16
	v_mul_f32_e32 v235, 0xbfb8aa3b, v17
	v_mul_f32_e32 v236, 0xbfb8aa3b, v18
	v_mul_f32_e32 v237, 0xbfb8aa3b, v19
	v_exp_f32_e32 v230, v230
	v_exp_f32_e32 v231, v231
	v_exp_f32_e32 v232, v232
	v_exp_f32_e32 v233, v233
	v_exp_f32_e32 v234, v234
	v_exp_f32_e32 v235, v235
	v_exp_f32_e32 v236, v236
	v_exp_f32_e32 v237, v237
	v_add_f32_e32 v230, 1.0, v230
	v_add_f32_e32 v231, 1.0, v231
	v_add_f32_e32 v232, 1.0, v232
	v_add_f32_e32 v233, 1.0, v233
	v_add_f32_e32 v234, 1.0, v234
	v_add_f32_e32 v235, 1.0, v235
	v_add_f32_e32 v236, 1.0, v236
	v_add_f32_e32 v237, 1.0, v237
	v_rcp_f32_e32 v230, v230
	v_rcp_f32_e32 v231, v231
	v_rcp_f32_e32 v232, v232
	v_rcp_f32_e32 v233, v233
	v_rcp_f32_e32 v234, v234
	v_rcp_f32_e32 v235, v235
	v_rcp_f32_e32 v236, v236
	v_rcp_f32_e32 v237, v237
	v_lshlrev_b32_e32 v238, 16, v158
	v_and_b32_e32 v239, 0xffff0000, v158
	v_lshlrev_b32_e32 v240, 16, v159
	v_and_b32_e32 v241, 0xffff0000, v159
	v_lshlrev_b32_e32 v242, 16, v160
	v_and_b32_e32 v243, 0xffff0000, v160
	v_lshlrev_b32_e32 v244, 16, v161
	v_and_b32_e32 v245, 0xffff0000, v161
	v_pk_fma_f32 v[170:171], v[230:231], v[238:239], v[170:171]
	v_pk_fma_f32 v[172:173], v[232:233], v[240:241], v[172:173]
	v_pk_fma_f32 v[174:175], v[234:235], v[242:243], v[174:175]
	v_pk_fma_f32 v[176:177], v[236:237], v[244:245], v[176:177]
	global_store_dwordx4 v[202:203], v[162:165], off
	v_lshl_add_u64 v[202:203], v[202:203], 0, s[8:9]
	global_store_dwordx4 v[202:203], v[166:169], off
	v_lshl_add_u64 v[202:203], v[202:203], 0, s[8:9]
	global_store_dwordx4 v[202:203], v[170:173], off
	v_lshl_add_u64 v[202:203], v[202:203], 0, s[8:9]
	global_store_dwordx4 v[202:203], v[174:177], off
	v_lshl_add_u64 v[202:203], v[202:203], 0, s[8:9]
	s_waitcnt vmcnt(8)
	v_mul_f32_e32 v230, 0xbfb8aa3b, v12
	v_mul_f32_e32 v231, 0xbfb8aa3b, v13
	v_mul_f32_e32 v232, 0xbfb8aa3b, v14
	v_mul_f32_e32 v233, 0xbfb8aa3b, v15
	v_mul_f32_e32 v234, 0xbfb8aa3b, v8
	v_mul_f32_e32 v235, 0xbfb8aa3b, v9
	v_mul_f32_e32 v236, 0xbfb8aa3b, v10
	v_mul_f32_e32 v237, 0xbfb8aa3b, v11
	v_exp_f32_e32 v230, v230
	v_exp_f32_e32 v231, v231
	v_exp_f32_e32 v232, v232
	v_exp_f32_e32 v233, v233
	v_exp_f32_e32 v234, v234
	v_exp_f32_e32 v235, v235
	v_exp_f32_e32 v236, v236
	v_exp_f32_e32 v237, v237
	v_add_f32_e32 v230, 1.0, v230
	v_add_f32_e32 v231, 1.0, v231
	v_add_f32_e32 v232, 1.0, v232
	v_add_f32_e32 v233, 1.0, v233
	v_add_f32_e32 v234, 1.0, v234
	v_add_f32_e32 v235, 1.0, v235
	v_add_f32_e32 v236, 1.0, v236
	v_add_f32_e32 v237, 1.0, v237
	v_rcp_f32_e32 v230, v230
	v_rcp_f32_e32 v231, v231
	v_rcp_f32_e32 v232, v232
	v_rcp_f32_e32 v233, v233
	v_rcp_f32_e32 v234, v234
	v_rcp_f32_e32 v235, v235
	v_rcp_f32_e32 v236, v236
	v_rcp_f32_e32 v237, v237
	v_lshlrev_b32_e32 v238, 16, v178
	v_and_b32_e32 v239, 0xffff0000, v178
	v_lshlrev_b32_e32 v240, 16, v179
	v_and_b32_e32 v241, 0xffff0000, v179
	v_lshlrev_b32_e32 v242, 16, v180
	v_and_b32_e32 v243, 0xffff0000, v180
	v_lshlrev_b32_e32 v244, 16, v181
	v_and_b32_e32 v245, 0xffff0000, v181
	v_pk_fma_f32 v[186:187], v[230:231], v[238:239], v[186:187]
	v_pk_fma_f32 v[188:189], v[232:233], v[240:241], v[188:189]
	v_pk_fma_f32 v[190:191], v[234:235], v[242:243], v[190:191]
	v_pk_fma_f32 v[192:193], v[236:237], v[244:245], v[192:193]
	v_mul_f32_e32 v230, 0xbfb8aa3b, v4
	v_mul_f32_e32 v231, 0xbfb8aa3b, v5
	v_mul_f32_e32 v232, 0xbfb8aa3b, v6
	v_mul_f32_e32 v233, 0xbfb8aa3b, v7
	v_mul_f32_e32 v234, 0xbfb8aa3b, v0
	v_mul_f32_e32 v235, 0xbfb8aa3b, v1
	v_mul_f32_e32 v236, 0xbfb8aa3b, v2
	v_mul_f32_e32 v237, 0xbfb8aa3b, v3
	v_exp_f32_e32 v230, v230
	v_exp_f32_e32 v231, v231
	v_exp_f32_e32 v232, v232
	v_exp_f32_e32 v233, v233
	v_exp_f32_e32 v234, v234
	v_exp_f32_e32 v235, v235
	v_exp_f32_e32 v236, v236
	v_exp_f32_e32 v237, v237
	v_add_f32_e32 v230, 1.0, v230
	v_add_f32_e32 v231, 1.0, v231
	v_add_f32_e32 v232, 1.0, v232
	v_add_f32_e32 v233, 1.0, v233
	v_add_f32_e32 v234, 1.0, v234
	v_add_f32_e32 v235, 1.0, v235
	v_add_f32_e32 v236, 1.0, v236
	v_add_f32_e32 v237, 1.0, v237
	v_rcp_f32_e32 v230, v230
	v_rcp_f32_e32 v231, v231
	v_rcp_f32_e32 v232, v232
	v_rcp_f32_e32 v233, v233
	v_rcp_f32_e32 v234, v234
	v_rcp_f32_e32 v235, v235
	v_rcp_f32_e32 v236, v236
	v_rcp_f32_e32 v237, v237
	v_lshlrev_b32_e32 v238, 16, v182
	v_and_b32_e32 v239, 0xffff0000, v182
	v_lshlrev_b32_e32 v240, 16, v183
	v_and_b32_e32 v241, 0xffff0000, v183
	v_lshlrev_b32_e32 v242, 16, v184
	v_and_b32_e32 v243, 0xffff0000, v184
	v_lshlrev_b32_e32 v244, 16, v185
	v_and_b32_e32 v245, 0xffff0000, v185
	v_pk_fma_f32 v[194:195], v[230:231], v[238:239], v[194:195]
	v_pk_fma_f32 v[196:197], v[232:233], v[240:241], v[196:197]
	v_pk_fma_f32 v[198:199], v[234:235], v[242:243], v[198:199]
	v_pk_fma_f32 v[200:201], v[236:237], v[244:245], v[200:201]
	global_store_dwordx4 v[202:203], v[186:189], off
	v_lshl_add_u64 v[202:203], v[202:203], 0, s[8:9]
	global_store_dwordx4 v[202:203], v[190:193], off
	v_lshl_add_u64 v[202:203], v[202:203], 0, s[8:9]
	global_store_dwordx4 v[202:203], v[194:197], off
	v_lshl_add_u64 v[202:203], v[202:203], 0, s[8:9]
	global_store_dwordx4 v[202:203], v[198:201], off
	v_lshl_add_u64 v[202:203], v[202:203], 0, s[8:9]
	s_branch .LBB0_360
.Lgepi_2:
	v_mov_b64_e32 v[248:249], v[142:143]
	s_mov_b64 s[14:15], 0x10000
	v_ashrrev_i32_e32 v123, 7, v228
	v_and_b32_e32 v127, 64, v228
	v_lshrrev_b32_e32 v129, 2, v228
	v_and_or_b32 v146, v228, 15, s70
	v_mov_b32_e32 v147, 0
	v_mad_u64_u32 v[146:147], s[6:7], v123, s39, v[146:147]
	v_and_b32_e32 v129, 12, v129
	v_or3_b32 v148, v127, v129, s76
	v_mov_b32_e32 v149, 0
	v_lshl_add_u64 v[148:149], v[148:149], 1, s[96:97]
	v_lshlrev_b64 v[146:147], 12, v[146:147]
	v_lshl_add_u64 v[148:149], v[148:149], 0, v[146:147]
	global_load_dwordx4 v[98:101], v[246:247], off
	v_lshl_add_u64 v[246:247], v[246:247], 0, s[8:9]
	global_load_dwordx4 v[102:105], v[246:247], off
	v_lshl_add_u64 v[246:247], v[246:247], 0, s[8:9]
	global_load_dwordx4 v[106:109], v[248:249], off
	v_lshl_add_u64 v[248:249], v[248:249], 0, s[8:9]
	global_load_dwordx4 v[110:113], v[248:249], off
	v_lshl_add_u64 v[248:249], v[248:249], 0, s[8:9]
	global_load_dwordx4 v[114:117], v[248:249], off
	v_lshl_add_u64 v[248:249], v[248:249], 0, s[8:9]
	global_load_dwordx4 v[118:121], v[248:249], off
	v_lshl_add_u64 v[248:249], v[248:249], 0, s[8:9]
	global_load_dwordx4 v[154:157], v[246:247], off
	v_lshl_add_u64 v[246:247], v[246:247], 0, s[8:9]
	global_load_dwordx4 v[158:161], v[246:247], off
	v_lshl_add_u64 v[246:247], v[246:247], 0, s[8:9]
	global_load_dwordx4 v[162:165], v[248:249], off
	v_lshl_add_u64 v[248:249], v[248:249], 0, s[8:9]
	global_load_dwordx4 v[166:169], v[248:249], off
	v_lshl_add_u64 v[248:249], v[248:249], 0, s[8:9]
	global_load_dwordx4 v[170:173], v[248:249], off
	v_lshl_add_u64 v[248:249], v[248:249], 0, s[8:9]
	global_load_dwordx4 v[174:177], v[248:249], off
	v_lshl_add_u64 v[248:249], v[248:249], 0, s[8:9]
	global_load_dwordx4 v[178:181], v[246:247], off
	v_lshl_add_u64 v[246:247], v[246:247], 0, s[8:9]
	global_load_dwordx4 v[182:185], v[246:247], off
	v_lshl_add_u64 v[246:247], v[246:247], 0, s[8:9]
	global_load_dwordx4 v[186:189], v[248:249], off
	v_lshl_add_u64 v[248:249], v[248:249], 0, s[8:9]
	global_load_dwordx4 v[190:193], v[248:249], off
	v_lshl_add_u64 v[248:249], v[248:249], 0, s[8:9]
	global_load_dwordx4 v[194:197], v[248:249], off
	v_lshl_add_u64 v[248:249], v[248:249], 0, s[8:9]
	global_load_dwordx4 v[198:201], v[248:249], off
	v_lshl_add_u64 v[248:249], v[248:249], 0, s[8:9]
	s_waitcnt vmcnt(12)
	v_mul_f32_e32 v230, 0xbfb8aa3b, v92
	v_mul_f32_e32 v231, 0xbfb8aa3b, v93
	v_mul_f32_e32 v232, 0xbfb8aa3b, v94
	v_mul_f32_e32 v233, 0xbfb8aa3b, v95
	v_mul_f32_e32 v234, 0xbfb8aa3b, v88
	v_mul_f32_e32 v235, 0xbfb8aa3b, v89
	v_mul_f32_e32 v236, 0xbfb8aa3b, v90
	v_mul_f32_e32 v237, 0xbfb8aa3b, v91
	v_exp_f32_e32 v230, v230
	v_exp_f32_e32 v231, v231
	v_exp_f32_e32 v232, v232
	v_exp_f32_e32 v233, v233
	v_exp_f32_e32 v234, v234
	v_exp_f32_e32 v235, v235
	v_exp_f32_e32 v236, v236
	v_exp_f32_e32 v237, v237
	v_add_f32_e32 v230, 1.0, v230
	v_add_f32_e32 v231, 1.0, v231
	v_add_f32_e32 v232, 1.0, v232
	v_add_f32_e32 v233, 1.0, v233
	v_add_f32_e32 v234, 1.0, v234
	v_add_f32_e32 v235, 1.0, v235
	v_add_f32_e32 v236, 1.0, v236
	v_add_f32_e32 v237, 1.0, v237
	v_rcp_f32_e32 v230, v230
	v_rcp_f32_e32 v231, v231
	v_rcp_f32_e32 v232, v232
	v_rcp_f32_e32 v233, v233
	v_rcp_f32_e32 v234, v234
	v_rcp_f32_e32 v235, v235
	v_rcp_f32_e32 v236, v236
	v_rcp_f32_e32 v237, v237
	v_lshlrev_b32_e32 v238, 16, v98
	v_and_b32_e32 v239, 0xffff0000, v98
	v_lshlrev_b32_e32 v240, 16, v99
	v_and_b32_e32 v241, 0xffff0000, v99
	v_lshlrev_b32_e32 v242, 16, v100
	v_and_b32_e32 v243, 0xffff0000, v100
	v_lshlrev_b32_e32 v244, 16, v101
	v_and_b32_e32 v245, 0xffff0000, v101
	v_pk_fma_f32 v[106:107], v[230:231], v[238:239], v[106:107]
	v_pk_fma_f32 v[108:109], v[232:233], v[240:241], v[108:109]
	v_pk_fma_f32 v[110:111], v[234:235], v[242:243], v[110:111]
	v_pk_fma_f32 v[112:113], v[236:237], v[244:245], v[112:113]
	v_mul_f32_e32 v230, 0xbfb8aa3b, v84
	v_mul_f32_e32 v231, 0xbfb8aa3b, v85
	v_mul_f32_e32 v232, 0xbfb8aa3b, v86
	v_mul_f32_e32 v233, 0xbfb8aa3b, v87
	v_mul_f32_e32 v234, 0xbfb8aa3b, v80
	v_mul_f32_e32 v235, 0xbfb8aa3b, v81
	v_mul_f32_e32 v236, 0xbfb8aa3b, v82
	v_mul_f32_e32 v237, 0xbfb8aa3b, v83
	v_exp_f32_e32 v230, v230
	v_exp_f32_e32 v231, v231
	v_exp_f32_e32 v232, v232
	v_exp_f32_e32 v233, v233
	v_exp_f32_e32 v234, v234
	v_exp_f32_e32 v235, v235
	v_exp_f32_e32 v236, v236
	v_exp_f32_e32 v237, v237
	v_add_f32_e32 v230, 1.0, v230
	v_add_f32_e32 v231, 1.0, v231
	v_add_f32_e32 v232, 1.0, v232
	v_add_f32_e32 v233, 1.0, v233
	v_add_f32_e32 v234, 1.0, v234
	v_add_f32_e32 v235, 1.0, v235
	v_add_f32_e32 v236, 1.0, v236
	v_add_f32_e32 v237, 1.0, v237
	v_rcp_f32_e32 v230, v230
	v_rcp_f32_e32 v231, v231
	v_rcp_f32_e32 v232, v232
	v_rcp_f32_e32 v233, v233
	v_rcp_f32_e32 v234, v234
	v_rcp_f32_e32 v235, v235
	v_rcp_f32_e32 v236, v236
	v_rcp_f32_e32 v237, v237
	v_lshlrev_b32_e32 v238, 16, v102
	v_and_b32_e32 v239, 0xffff0000, v102
	v_lshlrev_b32_e32 v240, 16, v103
	v_and_b32_e32 v241, 0xffff0000, v103
	v_lshlrev_b32_e32 v242, 16, v104
	v_and_b32_e32 v243, 0xffff0000, v104
	v_lshlrev_b32_e32 v244, 16, v105
	v_and_b32_e32 v245, 0xffff0000, v105
	v_pk_fma_f32 v[114:115], v[230:231], v[238:239], v[114:115]
	v_pk_fma_f32 v[116:117], v[232:233], v[240:241], v[116:117]
	v_pk_fma_f32 v[118:119], v[234:235], v[242:243], v[118:119]
	v_pk_fma_f32 v[120:121], v[236:237], v[244:245], v[120:121]
	v_cvt_pk_bf16_f32 v230, v106, v107
	v_cvt_pk_bf16_f32 v231, v108, v109
	v_cvt_pk_bf16_f32 v232, v110, v111
	v_cvt_pk_bf16_f32 v233, v112, v113
	v_cvt_pk_bf16_f32 v234, v114, v115
	v_cvt_pk_bf16_f32 v235, v116, v117
	v_cvt_pk_bf16_f32 v236, v118, v119
	v_cvt_pk_bf16_f32 v237, v120, v121
	global_store_dwordx2 v[148:149], v[230:231], off
	global_store_dwordx2 v[148:149], v[232:233], off offset:32
	global_store_dwordx2 v[148:149], v[234:235], off offset:64
	global_store_dwordx2 v[148:149], v[236:237], off offset:96
	v_lshl_add_u64 v[148:149], v[148:149], 0, s[14:15]
	global_load_dwordx4 v[98:101], v[246:247], off
	v_lshl_add_u64 v[246:247], v[246:247], 0, s[8:9]
	global_load_dwordx4 v[102:105], v[246:247], off
	v_lshl_add_u64 v[246:247], v[246:247], 0, s[8:9]
	global_load_dwordx4 v[106:109], v[248:249], off
	v_lshl_add_u64 v[248:249], v[248:249], 0, s[8:9]
	global_load_dwordx4 v[110:113], v[248:249], off
	v_lshl_add_u64 v[248:249], v[248:249], 0, s[8:9]
	global_load_dwordx4 v[114:117], v[248:249], off
	v_lshl_add_u64 v[248:249], v[248:249], 0, s[8:9]
	global_load_dwordx4 v[118:121], v[248:249], off
	v_lshl_add_u64 v[248:249], v[248:249], 0, s[8:9]
	s_waitcnt vmcnt(16)
	v_mul_f32_e32 v230, 0xbfb8aa3b, v76
	v_mul_f32_e32 v231, 0xbfb8aa3b, v77
	v_mul_f32_e32 v232, 0xbfb8aa3b, v78
	v_mul_f32_e32 v233, 0xbfb8aa3b, v79
	v_mul_f32_e32 v234, 0xbfb8aa3b, v72
	v_mul_f32_e32 v235, 0xbfb8aa3b, v73
	v_mul_f32_e32 v236, 0xbfb8aa3b, v74
	v_mul_f32_e32 v237, 0xbfb8aa3b, v75
	v_exp_f32_e32 v230, v230
	v_exp_f32_e32 v231, v231
	v_exp_f32_e32 v232, v232
	v_exp_f32_e32 v233, v233
	v_exp_f32_e32 v234, v234
	v_exp_f32_e32 v235, v235
	v_exp_f32_e32 v236, v236
	v_exp_f32_e32 v237, v237
	v_add_f32_e32 v230, 1.0, v230
	v_add_f32_e32 v231, 1.0, v231
	v_add_f32_e32 v232, 1.0, v232
	v_add_f32_e32 v233, 1.0, v233
	v_add_f32_e32 v234, 1.0, v234
	v_add_f32_e32 v235, 1.0, v235
	v_add_f32_e32 v236, 1.0, v236
	v_add_f32_e32 v237, 1.0, v237
	v_rcp_f32_e32 v230, v230
	v_rcp_f32_e32 v231, v231
	v_rcp_f32_e32 v232, v232
	v_rcp_f32_e32 v233, v233
	v_rcp_f32_e32 v234, v234
	v_rcp_f32_e32 v235, v235
	v_rcp_f32_e32 v236, v236
	v_rcp_f32_e32 v237, v237
	v_lshlrev_b32_e32 v238, 16, v154
	v_and_b32_e32 v239, 0xffff0000, v154
	v_lshlrev_b32_e32 v240, 16, v155
	v_and_b32_e32 v241, 0xffff0000, v155
	v_lshlrev_b32_e32 v242, 16, v156
	v_and_b32_e32 v243, 0xffff0000, v156
	v_lshlrev_b32_e32 v244, 16, v157
	v_and_b32_e32 v245, 0xffff0000, v157
	v_pk_fma_f32 v[162:163], v[230:231], v[238:239], v[162:163]
	v_pk_fma_f32 v[164:165], v[232:233], v[240:241], v[164:165]
	v_pk_fma_f32 v[166:167], v[234:235], v[242:243], v[166:167]
	v_pk_fma_f32 v[168:169], v[236:237], v[244:245], v[168:169]
	v_mul_f32_e32 v230, 0xbfb8aa3b, v68
	v_mul_f32_e32 v231, 0xbfb8aa3b, v69
	v_mul_f32_e32 v232, 0xbfb8aa3b, v70
	v_mul_f32_e32 v233, 0xbfb8aa3b, v71
	v_mul_f32_e32 v234, 0xbfb8aa3b, v64
	v_mul_f32_e32 v235, 0xbfb8aa3b, v65
	v_mul_f32_e32 v236, 0xbfb8aa3b, v66
	v_mul_f32_e32 v237, 0xbfb8aa3b, v67
	v_exp_f32_e32 v230, v230
	v_exp_f32_e32 v231, v231
	v_exp_f32_e32 v232, v232
	v_exp_f32_e32 v233, v233
	v_exp_f32_e32 v234, v234
	v_exp_f32_e32 v235, v235
	v_exp_f32_e32 v236, v236
	v_exp_f32_e32 v237, v237
	v_add_f32_e32 v230, 1.0, v230
	v_add_f32_e32 v231, 1.0, v231
	v_add_f32_e32 v232, 1.0, v232
	v_add_f32_e32 v233, 1.0, v233
	v_add_f32_e32 v234, 1.0, v234
	v_add_f32_e32 v235, 1.0, v235
	v_add_f32_e32 v236, 1.0, v236
	v_add_f32_e32 v237, 1.0, v237
	v_rcp_f32_e32 v230, v230
	v_rcp_f32_e32 v231, v231
	v_rcp_f32_e32 v232, v232
	v_rcp_f32_e32 v233, v233
	v_rcp_f32_e32 v234, v234
	v_rcp_f32_e32 v235, v235
	v_rcp_f32_e32 v236, v236
	v_rcp_f32_e32 v237, v237
	v_lshlrev_b32_e32 v238, 16, v158
	v_and_b32_e32 v239, 0xffff0000, v158
	v_lshlrev_b32_e32 v240, 16, v159
	v_and_b32_e32 v241, 0xffff0000, v159
	v_lshlrev_b32_e32 v242, 16, v160
	v_and_b32_e32 v243, 0xffff0000, v160
	v_lshlrev_b32_e32 v244, 16, v161
	v_and_b32_e32 v245, 0xffff0000, v161
	v_pk_fma_f32 v[170:171], v[230:231], v[238:239], v[170:171]
	v_pk_fma_f32 v[172:173], v[232:233], v[240:241], v[172:173]
	v_pk_fma_f32 v[174:175], v[234:235], v[242:243], v[174:175]
	v_pk_fma_f32 v[176:177], v[236:237], v[244:245], v[176:177]
	v_cvt_pk_bf16_f32 v230, v162, v163
	v_cvt_pk_bf16_f32 v231, v164, v165
	v_cvt_pk_bf16_f32 v232, v166, v167
	v_cvt_pk_bf16_f32 v233, v168, v169
	v_cvt_pk_bf16_f32 v234, v170, v171
	v_cvt_pk_bf16_f32 v235, v172, v173
	v_cvt_pk_bf16_f32 v236, v174, v175
	v_cvt_pk_bf16_f32 v237, v176, v177
	global_store_dwordx2 v[148:149], v[230:231], off
	global_store_dwordx2 v[148:149], v[232:233], off offset:32
	global_store_dwordx2 v[148:149], v[234:235], off offset:64
	global_store_dwordx2 v[148:149], v[236:237], off offset:96
	v_lshl_add_u64 v[148:149], v[148:149], 0, s[14:15]
	global_load_dwordx4 v[154:157], v[246:247], off
	v_lshl_add_u64 v[246:247], v[246:247], 0, s[8:9]
	global_load_dwordx4 v[158:161], v[246:247], off
	v_lshl_add_u64 v[246:247], v[246:247], 0, s[8:9]
	global_load_dwordx4 v[162:165], v[248:249], off
	v_lshl_add_u64 v[248:249], v[248:249], 0, s[8:9]
	global_load_dwordx4 v[166:169], v[248:249], off
	v_lshl_add_u64 v[248:249], v[248:249], 0, s[8:9]
	global_load_dwordx4 v[170:173], v[248:249], off
	v_lshl_add_u64 v[248:249], v[248:249], 0, s[8:9]
	global_load_dwordx4 v[174:177], v[248:249], off
	v_lshl_add_u64 v[248:249], v[248:249], 0, s[8:9]
	s_waitcnt vmcnt(20)
	v_mul_f32_e32 v230, 0xbfb8aa3b, v60
	v_mul_f32_e32 v231, 0xbfb8aa3b, v61
	v_mul_f32_e32 v232, 0xbfb8aa3b, v62
	v_mul_f32_e32 v233, 0xbfb8aa3b, v63
	v_mul_f32_e32 v234, 0xbfb8aa3b, v56
	v_mul_f32_e32 v235, 0xbfb8aa3b, v57
	v_mul_f32_e32 v236, 0xbfb8aa3b, v58
	v_mul_f32_e32 v237, 0xbfb8aa3b, v59
	v_exp_f32_e32 v230, v230
	v_exp_f32_e32 v231, v231
	v_exp_f32_e32 v232, v232
	v_exp_f32_e32 v233, v233
	v_exp_f32_e32 v234, v234
	v_exp_f32_e32 v235, v235
	v_exp_f32_e32 v236, v236
	v_exp_f32_e32 v237, v237
	v_add_f32_e32 v230, 1.0, v230
	v_add_f32_e32 v231, 1.0, v231
	v_add_f32_e32 v232, 1.0, v232
	v_add_f32_e32 v233, 1.0, v233
	v_add_f32_e32 v234, 1.0, v234
	v_add_f32_e32 v235, 1.0, v235
	v_add_f32_e32 v236, 1.0, v236
	v_add_f32_e32 v237, 1.0, v237
	v_rcp_f32_e32 v230, v230
	v_rcp_f32_e32 v231, v231
	v_rcp_f32_e32 v232, v232
	v_rcp_f32_e32 v233, v233
	v_rcp_f32_e32 v234, v234
	v_rcp_f32_e32 v235, v235
	v_rcp_f32_e32 v236, v236
	v_rcp_f32_e32 v237, v237
	v_lshlrev_b32_e32 v238, 16, v178
	v_and_b32_e32 v239, 0xffff0000, v178
	v_lshlrev_b32_e32 v240, 16, v179
	v_and_b32_e32 v241, 0xffff0000, v179
	v_lshlrev_b32_e32 v242, 16, v180
	v_and_b32_e32 v243, 0xffff0000, v180
	v_lshlrev_b32_e32 v244, 16, v181
	v_and_b32_e32 v245, 0xffff0000, v181
	v_pk_fma_f32 v[186:187], v[230:231], v[238:239], v[186:187]
	v_pk_fma_f32 v[188:189], v[232:233], v[240:241], v[188:189]
	v_pk_fma_f32 v[190:191], v[234:235], v[242:243], v[190:191]
	v_pk_fma_f32 v[192:193], v[236:237], v[244:245], v[192:193]
	v_mul_f32_e32 v230, 0xbfb8aa3b, v52
	v_mul_f32_e32 v231, 0xbfb8aa3b, v53
	v_mul_f32_e32 v232, 0xbfb8aa3b, v54
	v_mul_f32_e32 v233, 0xbfb8aa3b, v55
	v_mul_f32_e32 v234, 0xbfb8aa3b, v48
	v_mul_f32_e32 v235, 0xbfb8aa3b, v49
	v_mul_f32_e32 v236, 0xbfb8aa3b, v50
	v_mul_f32_e32 v237, 0xbfb8aa3b, v51
	v_exp_f32_e32 v230, v230
	v_exp_f32_e32 v231, v231
	v_exp_f32_e32 v232, v232
	v_exp_f32_e32 v233, v233
	v_exp_f32_e32 v234, v234
	v_exp_f32_e32 v235, v235
	v_exp_f32_e32 v236, v236
	v_exp_f32_e32 v237, v237
	v_add_f32_e32 v230, 1.0, v230
	v_add_f32_e32 v231, 1.0, v231
	v_add_f32_e32 v232, 1.0, v232
	v_add_f32_e32 v233, 1.0, v233
	v_add_f32_e32 v234, 1.0, v234
	v_add_f32_e32 v235, 1.0, v235
	v_add_f32_e32 v236, 1.0, v236
	v_add_f32_e32 v237, 1.0, v237
	v_rcp_f32_e32 v230, v230
	v_rcp_f32_e32 v231, v231
	v_rcp_f32_e32 v232, v232
	v_rcp_f32_e32 v233, v233
	v_rcp_f32_e32 v234, v234
	v_rcp_f32_e32 v235, v235
	v_rcp_f32_e32 v236, v236
	v_rcp_f32_e32 v237, v237
	v_lshlrev_b32_e32 v238, 16, v182
	v_and_b32_e32 v239, 0xffff0000, v182
	v_lshlrev_b32_e32 v240, 16, v183
	v_and_b32_e32 v241, 0xffff0000, v183
	v_lshlrev_b32_e32 v242, 16, v184
	v_and_b32_e32 v243, 0xffff0000, v184
	v_lshlrev_b32_e32 v244, 16, v185
	v_and_b32_e32 v245, 0xffff0000, v185
	v_pk_fma_f32 v[194:195], v[230:231], v[238:239], v[194:195]
	v_pk_fma_f32 v[196:197], v[232:233], v[240:241], v[196:197]
	v_pk_fma_f32 v[198:199], v[234:235], v[242:243], v[198:199]
	v_pk_fma_f32 v[200:201], v[236:237], v[244:245], v[200:201]
	v_cvt_pk_bf16_f32 v230, v186, v187
	v_cvt_pk_bf16_f32 v231, v188, v189
	v_cvt_pk_bf16_f32 v232, v190, v191
	v_cvt_pk_bf16_f32 v233, v192, v193
	v_cvt_pk_bf16_f32 v234, v194, v195
	v_cvt_pk_bf16_f32 v235, v196, v197
	v_cvt_pk_bf16_f32 v236, v198, v199
	v_cvt_pk_bf16_f32 v237, v200, v201
	global_store_dwordx2 v[148:149], v[230:231], off
	global_store_dwordx2 v[148:149], v[232:233], off offset:32
	global_store_dwordx2 v[148:149], v[234:235], off offset:64
	global_store_dwordx2 v[148:149], v[236:237], off offset:96
	v_lshl_add_u64 v[148:149], v[148:149], 0, s[14:15]
	global_load_dwordx4 v[178:181], v[246:247], off
	v_lshl_add_u64 v[246:247], v[246:247], 0, s[8:9]
	global_load_dwordx4 v[182:185], v[246:247], off
	v_lshl_add_u64 v[246:247], v[246:247], 0, s[8:9]
	global_load_dwordx4 v[186:189], v[248:249], off
	v_lshl_add_u64 v[248:249], v[248:249], 0, s[8:9]
	global_load_dwordx4 v[190:193], v[248:249], off
	v_lshl_add_u64 v[248:249], v[248:249], 0, s[8:9]
	global_load_dwordx4 v[194:197], v[248:249], off
	v_lshl_add_u64 v[248:249], v[248:249], 0, s[8:9]
	global_load_dwordx4 v[198:201], v[248:249], off
	v_lshl_add_u64 v[248:249], v[248:249], 0, s[8:9]
	s_waitcnt vmcnt(20)
	v_mul_f32_e32 v230, 0xbfb8aa3b, v44
	v_mul_f32_e32 v231, 0xbfb8aa3b, v45
	v_mul_f32_e32 v232, 0xbfb8aa3b, v46
	v_mul_f32_e32 v233, 0xbfb8aa3b, v47
	v_mul_f32_e32 v234, 0xbfb8aa3b, v40
	v_mul_f32_e32 v235, 0xbfb8aa3b, v41
	v_mul_f32_e32 v236, 0xbfb8aa3b, v42
	v_mul_f32_e32 v237, 0xbfb8aa3b, v43
	v_exp_f32_e32 v230, v230
	v_exp_f32_e32 v231, v231
	v_exp_f32_e32 v232, v232
	v_exp_f32_e32 v233, v233
	v_exp_f32_e32 v234, v234
	v_exp_f32_e32 v235, v235
	v_exp_f32_e32 v236, v236
	v_exp_f32_e32 v237, v237
	v_add_f32_e32 v230, 1.0, v230
	v_add_f32_e32 v231, 1.0, v231
	v_add_f32_e32 v232, 1.0, v232
	v_add_f32_e32 v233, 1.0, v233
	v_add_f32_e32 v234, 1.0, v234
	v_add_f32_e32 v235, 1.0, v235
	v_add_f32_e32 v236, 1.0, v236
	v_add_f32_e32 v237, 1.0, v237
	v_rcp_f32_e32 v230, v230
	v_rcp_f32_e32 v231, v231
	v_rcp_f32_e32 v232, v232
	v_rcp_f32_e32 v233, v233
	v_rcp_f32_e32 v234, v234
	v_rcp_f32_e32 v235, v235
	v_rcp_f32_e32 v236, v236
	v_rcp_f32_e32 v237, v237
	v_lshlrev_b32_e32 v238, 16, v98
	v_and_b32_e32 v239, 0xffff0000, v98
	v_lshlrev_b32_e32 v240, 16, v99
	v_and_b32_e32 v241, 0xffff0000, v99
	v_lshlrev_b32_e32 v242, 16, v100
	v_and_b32_e32 v243, 0xffff0000, v100
	v_lshlrev_b32_e32 v244, 16, v101
	v_and_b32_e32 v245, 0xffff0000, v101
	v_pk_fma_f32 v[106:107], v[230:231], v[238:239], v[106:107]
	v_pk_fma_f32 v[108:109], v[232:233], v[240:241], v[108:109]
	v_pk_fma_f32 v[110:111], v[234:235], v[242:243], v[110:111]
	v_pk_fma_f32 v[112:113], v[236:237], v[244:245], v[112:113]
	v_mul_f32_e32 v230, 0xbfb8aa3b, v36
	v_mul_f32_e32 v231, 0xbfb8aa3b, v37
	v_mul_f32_e32 v232, 0xbfb8aa3b, v38
	v_mul_f32_e32 v233, 0xbfb8aa3b, v39
	v_mul_f32_e32 v234, 0xbfb8aa3b, v32
	v_mul_f32_e32 v235, 0xbfb8aa3b, v33
	v_mul_f32_e32 v236, 0xbfb8aa3b, v34
	v_mul_f32_e32 v237, 0xbfb8aa3b, v35
	v_exp_f32_e32 v230, v230
	v_exp_f32_e32 v231, v231
	v_exp_f32_e32 v232, v232
	v_exp_f32_e32 v233, v233
	v_exp_f32_e32 v234, v234
	v_exp_f32_e32 v235, v235
	v_exp_f32_e32 v236, v236
	v_exp_f32_e32 v237, v237
	v_add_f32_e32 v230, 1.0, v230
	v_add_f32_e32 v231, 1.0, v231
	v_add_f32_e32 v232, 1.0, v232
	v_add_f32_e32 v233, 1.0, v233
	v_add_f32_e32 v234, 1.0, v234
	v_add_f32_e32 v235, 1.0, v235
	v_add_f32_e32 v236, 1.0, v236
	v_add_f32_e32 v237, 1.0, v237
	v_rcp_f32_e32 v230, v230
	v_rcp_f32_e32 v231, v231
	v_rcp_f32_e32 v232, v232
	v_rcp_f32_e32 v233, v233
	v_rcp_f32_e32 v234, v234
	v_rcp_f32_e32 v235, v235
	v_rcp_f32_e32 v236, v236
	v_rcp_f32_e32 v237, v237
	v_lshlrev_b32_e32 v238, 16, v102
	v_and_b32_e32 v239, 0xffff0000, v102
	v_lshlrev_b32_e32 v240, 16, v103
	v_and_b32_e32 v241, 0xffff0000, v103
	v_lshlrev_b32_e32 v242, 16, v104
	v_and_b32_e32 v243, 0xffff0000, v104
	v_lshlrev_b32_e32 v244, 16, v105
	v_and_b32_e32 v245, 0xffff0000, v105
	v_pk_fma_f32 v[114:115], v[230:231], v[238:239], v[114:115]
	v_pk_fma_f32 v[116:117], v[232:233], v[240:241], v[116:117]
	v_pk_fma_f32 v[118:119], v[234:235], v[242:243], v[118:119]
	v_pk_fma_f32 v[120:121], v[236:237], v[244:245], v[120:121]
	v_cvt_pk_bf16_f32 v230, v106, v107
	v_cvt_pk_bf16_f32 v231, v108, v109
	v_cvt_pk_bf16_f32 v232, v110, v111
	v_cvt_pk_bf16_f32 v233, v112, v113
	v_cvt_pk_bf16_f32 v234, v114, v115
	v_cvt_pk_bf16_f32 v235, v116, v117
	v_cvt_pk_bf16_f32 v236, v118, v119
	v_cvt_pk_bf16_f32 v237, v120, v121
	global_store_dwordx2 v[148:149], v[230:231], off
	global_store_dwordx2 v[148:149], v[232:233], off offset:32
	global_store_dwordx2 v[148:149], v[234:235], off offset:64
	global_store_dwordx2 v[148:149], v[236:237], off offset:96
	v_lshl_add_u64 v[148:149], v[148:149], 0, s[14:15]
	s_waitcnt vmcnt(14)
	v_mul_f32_e32 v230, 0xbfb8aa3b, v28
	v_mul_f32_e32 v231, 0xbfb8aa3b, v29
	v_mul_f32_e32 v232, 0xbfb8aa3b, v30
	v_mul_f32_e32 v233, 0xbfb8aa3b, v31
	v_mul_f32_e32 v234, 0xbfb8aa3b, v24
	v_mul_f32_e32 v235, 0xbfb8aa3b, v25
	v_mul_f32_e32 v236, 0xbfb8aa3b, v26
	v_mul_f32_e32 v237, 0xbfb8aa3b, v27
	v_exp_f32_e32 v230, v230
	v_exp_f32_e32 v231, v231
	v_exp_f32_e32 v232, v232
	v_exp_f32_e32 v233, v233
	v_exp_f32_e32 v234, v234
	v_exp_f32_e32 v235, v235
	v_exp_f32_e32 v236, v236
	v_exp_f32_e32 v237, v237
	v_add_f32_e32 v230, 1.0, v230
	v_add_f32_e32 v231, 1.0, v231
	v_add_f32_e32 v232, 1.0, v232
	v_add_f32_e32 v233, 1.0, v233
	v_add_f32_e32 v234, 1.0, v234
	v_add_f32_e32 v235, 1.0, v235
	v_add_f32_e32 v236, 1.0, v236
	v_add_f32_e32 v237, 1.0, v237
	v_rcp_f32_e32 v230, v230
	v_rcp_f32_e32 v231, v231
	v_rcp_f32_e32 v232, v232
	v_rcp_f32_e32 v233, v233
	v_rcp_f32_e32 v234, v234
	v_rcp_f32_e32 v235, v235
	v_rcp_f32_e32 v236, v236
	v_rcp_f32_e32 v237, v237
	v_lshlrev_b32_e32 v238, 16, v154
	v_and_b32_e32 v239, 0xffff0000, v154
	v_lshlrev_b32_e32 v240, 16, v155
	v_and_b32_e32 v241, 0xffff0000, v155
	v_lshlrev_b32_e32 v242, 16, v156
	v_and_b32_e32 v243, 0xffff0000, v156
	v_lshlrev_b32_e32 v244, 16, v157
	v_and_b32_e32 v245, 0xffff0000, v157
	v_pk_fma_f32 v[162:163], v[230:231], v[238:239], v[162:163]
	v_pk_fma_f32 v[164:165], v[232:233], v[240:241], v[164:165]
	v_pk_fma_f32 v[166:167], v[234:235], v[242:243], v[166:167]
	v_pk_fma_f32 v[168:169], v[236:237], v[244:245], v[168:169]
	v_mul_f32_e32 v230, 0xbfb8aa3b, v20
	v_mul_f32_e32 v231, 0xbfb8aa3b, v21
	v_mul_f32_e32 v232, 0xbfb8aa3b, v22
	v_mul_f32_e32 v233, 0xbfb8aa3b, v23
	v_mul_f32_e32 v234, 0xbfb8aa3b, v16
	v_mul_f32_e32 v235, 0xbfb8aa3b, v17
	v_mul_f32_e32 v236, 0xbfb8aa3b, v18
	v_mul_f32_e32 v237, 0xbfb8aa3b, v19
	v_exp_f32_e32 v230, v230
	v_exp_f32_e32 v231, v231
	v_exp_f32_e32 v232, v232
	v_exp_f32_e32 v233, v233
	v_exp_f32_e32 v234, v234
	v_exp_f32_e32 v235, v235
	v_exp_f32_e32 v236, v236
	v_exp_f32_e32 v237, v237
	v_add_f32_e32 v230, 1.0, v230
	v_add_f32_e32 v231, 1.0, v231
	v_add_f32_e32 v232, 1.0, v232
	v_add_f32_e32 v233, 1.0, v233
	v_add_f32_e32 v234, 1.0, v234
	v_add_f32_e32 v235, 1.0, v235
	v_add_f32_e32 v236, 1.0, v236
	v_add_f32_e32 v237, 1.0, v237
	v_rcp_f32_e32 v230, v230
	v_rcp_f32_e32 v231, v231
	v_rcp_f32_e32 v232, v232
	v_rcp_f32_e32 v233, v233
	v_rcp_f32_e32 v234, v234
	v_rcp_f32_e32 v235, v235
	v_rcp_f32_e32 v236, v236
	v_rcp_f32_e32 v237, v237
	v_lshlrev_b32_e32 v238, 16, v158
	v_and_b32_e32 v239, 0xffff0000, v158
	v_lshlrev_b32_e32 v240, 16, v159
	v_and_b32_e32 v241, 0xffff0000, v159
	v_lshlrev_b32_e32 v242, 16, v160
	v_and_b32_e32 v243, 0xffff0000, v160
	v_lshlrev_b32_e32 v244, 16, v161
	v_and_b32_e32 v245, 0xffff0000, v161
	v_pk_fma_f32 v[170:171], v[230:231], v[238:239], v[170:171]
	v_pk_fma_f32 v[172:173], v[232:233], v[240:241], v[172:173]
	v_pk_fma_f32 v[174:175], v[234:235], v[242:243], v[174:175]
	v_pk_fma_f32 v[176:177], v[236:237], v[244:245], v[176:177]
	v_cvt_pk_bf16_f32 v230, v162, v163
	v_cvt_pk_bf16_f32 v231, v164, v165
	v_cvt_pk_bf16_f32 v232, v166, v167
	v_cvt_pk_bf16_f32 v233, v168, v169
	v_cvt_pk_bf16_f32 v234, v170, v171
	v_cvt_pk_bf16_f32 v235, v172, v173
	v_cvt_pk_bf16_f32 v236, v174, v175
	v_cvt_pk_bf16_f32 v237, v176, v177
	global_store_dwordx2 v[148:149], v[230:231], off
	global_store_dwordx2 v[148:149], v[232:233], off offset:32
	global_store_dwordx2 v[148:149], v[234:235], off offset:64
	global_store_dwordx2 v[148:149], v[236:237], off offset:96
	v_lshl_add_u64 v[148:149], v[148:149], 0, s[14:15]
	s_waitcnt vmcnt(8)
	v_mul_f32_e32 v230, 0xbfb8aa3b, v12
	v_mul_f32_e32 v231, 0xbfb8aa3b, v13
	v_mul_f32_e32 v232, 0xbfb8aa3b, v14
	v_mul_f32_e32 v233, 0xbfb8aa3b, v15
	v_mul_f32_e32 v234, 0xbfb8aa3b, v8
	v_mul_f32_e32 v235, 0xbfb8aa3b, v9
	v_mul_f32_e32 v236, 0xbfb8aa3b, v10
	v_mul_f32_e32 v237, 0xbfb8aa3b, v11
	v_exp_f32_e32 v230, v230
	v_exp_f32_e32 v231, v231
	v_exp_f32_e32 v232, v232
	v_exp_f32_e32 v233, v233
	v_exp_f32_e32 v234, v234
	v_exp_f32_e32 v235, v235
	v_exp_f32_e32 v236, v236
	v_exp_f32_e32 v237, v237
	v_add_f32_e32 v230, 1.0, v230
	v_add_f32_e32 v231, 1.0, v231
	v_add_f32_e32 v232, 1.0, v232
	v_add_f32_e32 v233, 1.0, v233
	v_add_f32_e32 v234, 1.0, v234
	v_add_f32_e32 v235, 1.0, v235
	v_add_f32_e32 v236, 1.0, v236
	v_add_f32_e32 v237, 1.0, v237
	v_rcp_f32_e32 v230, v230
	v_rcp_f32_e32 v231, v231
	v_rcp_f32_e32 v232, v232
	v_rcp_f32_e32 v233, v233
	v_rcp_f32_e32 v234, v234
	v_rcp_f32_e32 v235, v235
	v_rcp_f32_e32 v236, v236
	v_rcp_f32_e32 v237, v237
	v_lshlrev_b32_e32 v238, 16, v178
	v_and_b32_e32 v239, 0xffff0000, v178
	v_lshlrev_b32_e32 v240, 16, v179
	v_and_b32_e32 v241, 0xffff0000, v179
	v_lshlrev_b32_e32 v242, 16, v180
	v_and_b32_e32 v243, 0xffff0000, v180
	v_lshlrev_b32_e32 v244, 16, v181
	v_and_b32_e32 v245, 0xffff0000, v181
	v_pk_fma_f32 v[186:187], v[230:231], v[238:239], v[186:187]
	v_pk_fma_f32 v[188:189], v[232:233], v[240:241], v[188:189]
	v_pk_fma_f32 v[190:191], v[234:235], v[242:243], v[190:191]
	v_pk_fma_f32 v[192:193], v[236:237], v[244:245], v[192:193]
	v_mul_f32_e32 v230, 0xbfb8aa3b, v4
	v_mul_f32_e32 v231, 0xbfb8aa3b, v5
	v_mul_f32_e32 v232, 0xbfb8aa3b, v6
	v_mul_f32_e32 v233, 0xbfb8aa3b, v7
	v_mul_f32_e32 v234, 0xbfb8aa3b, v0
	v_mul_f32_e32 v235, 0xbfb8aa3b, v1
	v_mul_f32_e32 v236, 0xbfb8aa3b, v2
	v_mul_f32_e32 v237, 0xbfb8aa3b, v3
	v_exp_f32_e32 v230, v230
	v_exp_f32_e32 v231, v231
	v_exp_f32_e32 v232, v232
	v_exp_f32_e32 v233, v233
	v_exp_f32_e32 v234, v234
	v_exp_f32_e32 v235, v235
	v_exp_f32_e32 v236, v236
	v_exp_f32_e32 v237, v237
	v_add_f32_e32 v230, 1.0, v230
	v_add_f32_e32 v231, 1.0, v231
	v_add_f32_e32 v232, 1.0, v232
	v_add_f32_e32 v233, 1.0, v233
	v_add_f32_e32 v234, 1.0, v234
	v_add_f32_e32 v235, 1.0, v235
	v_add_f32_e32 v236, 1.0, v236
	v_add_f32_e32 v237, 1.0, v237
	v_rcp_f32_e32 v230, v230
	v_rcp_f32_e32 v231, v231
	v_rcp_f32_e32 v232, v232
	v_rcp_f32_e32 v233, v233
	v_rcp_f32_e32 v234, v234
	v_rcp_f32_e32 v235, v235
	v_rcp_f32_e32 v236, v236
	v_rcp_f32_e32 v237, v237
	v_lshlrev_b32_e32 v238, 16, v182
	v_and_b32_e32 v239, 0xffff0000, v182
	v_lshlrev_b32_e32 v240, 16, v183
	v_and_b32_e32 v241, 0xffff0000, v183
	v_lshlrev_b32_e32 v242, 16, v184
	v_and_b32_e32 v243, 0xffff0000, v184
	v_lshlrev_b32_e32 v244, 16, v185
	v_and_b32_e32 v245, 0xffff0000, v185
	v_pk_fma_f32 v[194:195], v[230:231], v[238:239], v[194:195]
	v_pk_fma_f32 v[196:197], v[232:233], v[240:241], v[196:197]
	v_pk_fma_f32 v[198:199], v[234:235], v[242:243], v[198:199]
	v_pk_fma_f32 v[200:201], v[236:237], v[244:245], v[200:201]
	v_cvt_pk_bf16_f32 v230, v186, v187
	v_cvt_pk_bf16_f32 v231, v188, v189
	v_cvt_pk_bf16_f32 v232, v190, v191
	v_cvt_pk_bf16_f32 v233, v192, v193
	v_cvt_pk_bf16_f32 v234, v194, v195
	v_cvt_pk_bf16_f32 v235, v196, v197
	v_cvt_pk_bf16_f32 v236, v198, v199
	v_cvt_pk_bf16_f32 v237, v200, v201
	global_store_dwordx2 v[148:149], v[230:231], off
	global_store_dwordx2 v[148:149], v[232:233], off offset:32
	global_store_dwordx2 v[148:149], v[234:235], off offset:64
	global_store_dwordx2 v[148:149], v[236:237], off offset:96
	v_lshl_add_u64 v[148:149], v[148:149], 0, s[14:15]
	s_branch .LBB0_360

.LBB0_710:
	ds_read_b128 v[230:233], v182
	ds_read_b128 v[234:237], v183
	ds_read_b128 v[238:241], v184
	ds_read_b128 v[242:245], v185
	ds_read_b128 v[246:249], v182 offset:8192
	s_add_u32 s0, s0, 0x10000
	s_addc_u32 s1, s1, 0
	s_add_i32 s6, s6, 1
	v_lshl_add_u64 v[164:165], v[164:165], 0, s[64:65]
	v_lshl_add_u64 v[166:167], v[166:167], 0, s[64:65]
	v_lshl_add_u64 v[168:169], v[168:169], 0, s[64:65]
	v_lshl_add_u64 v[170:171], v[170:171], 0, s[64:65]
	s_cmp_eq_u32 s8, s0
	s_waitcnt lgkmcnt(4)
	v_mfma_f32_32x32x16_bf16 v[80:95], v[230:233], v[98:101], 0
	ds_read_b128 v[230:233], v183 offset:8192
	s_waitcnt lgkmcnt(4)
	v_mfma_f32_32x32x16_bf16 v[80:95], v[234:237], v[102:105], v[80:95]
	ds_read_b128 v[234:237], v184 offset:8192
	s_waitcnt lgkmcnt(4)
	v_mfma_f32_32x32x16_bf16 v[80:95], v[238:241], v[106:109], v[80:95]
	ds_read_b128 v[238:241], v185 offset:8192
	s_waitcnt lgkmcnt(4)
	v_mfma_f32_32x32x16_bf16 v[80:95], v[242:245], v[110:113], v[80:95]
	ds_read_b128 v[242:245], v186 offset:16384
	s_waitcnt lgkmcnt(4)
	v_mfma_f32_32x32x16_bf16 v[64:79], v[246:249], v[98:101], 0
	ds_read_b128 v[246:249], v186 offset:20480
	s_waitcnt lgkmcnt(4)
	v_mfma_f32_32x32x16_bf16 v[64:79], v[230:233], v[102:105], v[64:79]
	ds_read_b128 v[230:233], v186 offset:24576
	s_waitcnt lgkmcnt(4)
	v_mfma_f32_32x32x16_bf16 v[64:79], v[234:237], v[106:109], v[64:79]
	ds_read_b128 v[234:237], v186 offset:28672
	s_waitcnt lgkmcnt(4)
	v_mfma_f32_32x32x16_bf16 v[64:79], v[238:241], v[110:113], v[64:79]
	ds_read_b128 v[238:241], v187 offset:16384
	v_max_f32_e32 v191, v81, v81
	v_max_f32_e32 v192, v80, v80
	v_max_f32_e32 v191, v192, v191
	v_max3_f32 v191, v191, v82, v83
	v_max3_f32 v191, v191, v84, v85
	v_max3_f32 v191, v191, v86, v87
	v_max3_f32 v191, v191, v88, v89
	v_max3_f32 v191, v191, v90, v91
	v_max3_f32 v191, v191, v92, v93
	v_max3_f32 v191, v191, v94, v95
	s_nop 2
	v_max3_f32 v191, v191, v64, v65
	v_max3_f32 v191, v191, v66, v67
	v_max3_f32 v191, v191, v68, v69
	v_max3_f32 v191, v191, v70, v71
	v_max3_f32 v191, v191, v72, v73
	v_max3_f32 v191, v191, v74, v75
	v_max3_f32 v191, v191, v76, v77
	v_max3_f32 v191, v191, v78, v79
	ds_bpermute_b32 v192, v147, v191
	s_waitcnt lgkmcnt(0)
	v_max3_f32 v191, v172, v191, v192
	v_sub_f32_e32 v80, v80, v191
	v_exp_f32_e32 v192, v80
	v_sub_f32_e32 v81, v81, v191
	v_exp_f32_e32 v193, v81
	v_sub_f32_e32 v81, v82, v191
	v_exp_f32_e32 v194, v81
	v_sub_f32_e32 v81, v83, v191
	v_exp_f32_e32 v195, v81
	v_sub_f32_e32 v81, v84, v191
	v_add_f32_e32 v80, 0, v192
	v_exp_f32_e32 v196, v81
	v_sub_f32_e32 v81, v85, v191
	v_add_f32_e32 v80, v193, v80
	v_exp_f32_e32 v197, v81
	v_sub_f32_e32 v81, v86, v191
	v_add_f32_e32 v80, v194, v80
	v_exp_f32_e32 v198, v81
	v_sub_f32_e32 v81, v87, v191
	v_add_f32_e32 v80, v195, v80
	v_exp_f32_e32 v199, v81
	v_sub_f32_e32 v81, v88, v191
	v_add_f32_e32 v80, v196, v80
	v_exp_f32_e32 v88, v81
	v_sub_f32_e32 v81, v89, v191
	v_add_f32_e32 v80, v197, v80
	v_exp_f32_e32 v89, v81
	v_sub_f32_e32 v81, v90, v191
	v_add_f32_e32 v80, v198, v80
	v_exp_f32_e32 v90, v81
	v_sub_f32_e32 v81, v91, v191
	v_add_f32_e32 v80, v199, v80
	v_exp_f32_e32 v91, v81
	v_sub_f32_e32 v81, v92, v191
	v_add_f32_e32 v80, v88, v80
	v_exp_f32_e32 v92, v81
	v_sub_f32_e32 v81, v93, v191
	v_add_f32_e32 v80, v89, v80
	v_exp_f32_e32 v93, v81
	v_sub_f32_e32 v81, v94, v191
	v_add_f32_e32 v80, v90, v80
	v_exp_f32_e32 v94, v81
	v_sub_f32_e32 v81, v95, v191
	v_add_f32_e32 v80, v91, v80
	v_exp_f32_e32 v95, v81
	v_add_f32_e32 v80, v92, v80
	v_add_f32_e32 v80, v93, v80
	v_add_f32_e32 v80, v94, v80
	v_sub_f32_e32 v64, v64, v191
	v_add_f32_e32 v200, v95, v80
	v_exp_f32_e32 v80, v64
	v_sub_f32_e32 v64, v65, v191
	v_exp_f32_e32 v81, v64
	v_sub_f32_e32 v64, v66, v191
	v_exp_f32_e32 v82, v64
	v_sub_f32_e32 v64, v67, v191
	v_exp_f32_e32 v83, v64
	v_sub_f32_e32 v64, v68, v191
	v_exp_f32_e32 v84, v64
	v_sub_f32_e32 v64, v69, v191
	v_exp_f32_e32 v85, v64
	v_sub_f32_e32 v64, v70, v191
	v_exp_f32_e32 v86, v64
	v_sub_f32_e32 v64, v71, v191
	v_exp_f32_e32 v87, v64
	v_sub_f32_e32 v64, v72, v191
	v_exp_f32_e32 v69, v64
	v_sub_f32_e32 v64, v73, v191
	v_exp_f32_e32 v70, v64
	v_sub_f32_e32 v64, v74, v191
	v_exp_f32_e32 v71, v64
	v_sub_f32_e32 v64, v75, v191
	v_exp_f32_e32 v72, v64
	v_sub_f32_e32 v64, v76, v191
	v_exp_f32_e32 v73, v64
	v_sub_f32_e32 v64, v77, v191
	v_exp_f32_e32 v74, v64
	v_sub_f32_e32 v64, v78, v191
	v_exp_f32_e32 v75, v64
	v_sub_f32_e32 v64, v79, v191
	v_exp_f32_e32 v76, v64
	v_add_f32_e32 v64, v80, v200
	v_add_f32_e32 v64, v81, v64
	v_add_f32_e32 v64, v82, v64
	v_add_f32_e32 v64, v83, v64
	v_add_f32_e32 v64, v84, v64
	v_add_f32_e32 v64, v85, v64
	v_add_f32_e32 v64, v86, v64
	v_add_f32_e32 v64, v87, v64
	v_add_f32_e32 v64, v69, v64
	v_add_f32_e32 v64, v70, v64
	v_add_f32_e32 v64, v71, v64
	v_add_f32_e32 v64, v72, v64
	v_add_f32_e32 v64, v73, v64
	v_add_f32_e32 v64, v74, v64
	v_add_f32_e32 v64, v75, v64
	v_add_f32_e32 v68, v76, v64
	v_cvt_pk_bf16_f32 v64, v192, v193
	v_cvt_pk_bf16_f32 v65, v194, v195
	v_sub_f32_e32 v172, v172, v191
	v_exp_f32_e32 v172, v172
	v_cvt_pk_bf16_f32 v66, v196, v197
	v_cvt_pk_bf16_f32 v67, v198, v199
	v_pk_mul_f32 v[62:63], v[62:63], v[172:173] op_sel_hi:[1,0]
	v_pk_mul_f32 v[60:61], v[60:61], v[172:173] op_sel_hi:[1,0]
	v_pk_mul_f32 v[58:59], v[58:59], v[172:173] op_sel_hi:[1,0]
	v_pk_mul_f32 v[56:57], v[56:57], v[172:173] op_sel_hi:[1,0]
	v_pk_mul_f32 v[54:55], v[54:55], v[172:173] op_sel_hi:[1,0]
	v_pk_mul_f32 v[52:53], v[52:53], v[172:173] op_sel_hi:[1,0]
	v_pk_mul_f32 v[50:51], v[50:51], v[172:173] op_sel_hi:[1,0]
	v_pk_mul_f32 v[48:49], v[48:49], v[172:173] op_sel_hi:[1,0]
	v_pk_mul_f32 v[46:47], v[46:47], v[172:173] op_sel_hi:[1,0]
	v_pk_mul_f32 v[44:45], v[44:45], v[172:173] op_sel_hi:[1,0]
	s_waitcnt lgkmcnt(4)
	v_mfma_f32_32x32x16_bf16 v[48:63], v[242:245], v[64:67], v[48:63]
	ds_read_b128 v[242:245], v187 offset:20480
	v_mul_f32_e64 v42, v42, v172
	v_mul_f32_e64 v43, v43, v172
	v_mul_f32_e64 v40, v40, v172
	v_mul_f32_e64 v41, v41, v172
	v_pk_mul_f32 v[38:39], v[38:39], v[172:173] op_sel_hi:[1,0]
	v_pk_mul_f32 v[36:37], v[36:37], v[172:173] op_sel_hi:[1,0]
	v_pk_mul_f32 v[34:35], v[34:35], v[172:173] op_sel_hi:[1,0]
	v_pk_mul_f32 v[32:33], v[32:33], v[172:173] op_sel_hi:[1,0]
	v_pk_mul_f32 v[30:31], v[30:31], v[172:173] op_sel_hi:[1,0]
	v_pk_mul_f32 v[28:29], v[28:29], v[172:173] op_sel_hi:[1,0]
	s_waitcnt lgkmcnt(4)
	v_mfma_f32_32x32x16_bf16 v[32:47], v[246:249], v[64:67], v[32:47]
	ds_read_b128 v[246:249], v187 offset:24576
	v_mul_f32_e64 v26, v26, v172
	v_mul_f32_e64 v27, v27, v172
	v_mul_f32_e64 v24, v24, v172
	v_mul_f32_e64 v25, v25, v172
	v_pk_mul_f32 v[22:23], v[22:23], v[172:173] op_sel_hi:[1,0]
	v_pk_mul_f32 v[20:21], v[20:21], v[172:173] op_sel_hi:[1,0]
	v_pk_mul_f32 v[18:19], v[18:19], v[172:173] op_sel_hi:[1,0]
	v_pk_mul_f32 v[16:17], v[16:17], v[172:173] op_sel_hi:[1,0]
	v_pk_mul_f32 v[14:15], v[14:15], v[172:173] op_sel_hi:[1,0]
	v_pk_mul_f32 v[12:13], v[12:13], v[172:173] op_sel_hi:[1,0]
	s_waitcnt lgkmcnt(4)
	v_mfma_f32_32x32x16_bf16 v[16:31], v[230:233], v[64:67], v[16:31]
	ds_read_b128 v[230:233], v187 offset:28672
	v_mul_f32_e64 v10, v10, v172
	v_mul_f32_e64 v11, v11, v172
	v_mul_f32_e64 v8, v8, v172
	v_mul_f32_e64 v9, v9, v172
	v_pk_mul_f32 v[6:7], v[6:7], v[172:173] op_sel_hi:[1,0]
	v_pk_mul_f32 v[4:5], v[4:5], v[172:173] op_sel_hi:[1,0]
	v_pk_mul_f32 v[2:3], v[2:3], v[172:173] op_sel_hi:[1,0]
	v_pk_mul_f32 v[0:1], v[0:1], v[172:173] op_sel_hi:[1,0]
	v_fmac_f32_e32 v68, v190, v172
	s_waitcnt lgkmcnt(4)
	v_mfma_f32_32x32x16_bf16 v[0:15], v[234:237], v[64:67], v[0:15]
	ds_read_b128 v[234:237], v188 offset:16384
	v_cvt_pk_bf16_f32 v64, v88, v89
	v_cvt_pk_bf16_f32 v65, v90, v91
	v_cvt_pk_bf16_f32 v66, v92, v93
	v_cvt_pk_bf16_f32 v67, v94, v95
	s_waitcnt lgkmcnt(4)
	s_nop 0
	v_mfma_f32_32x32x16_bf16 v[48:63], v[238:241], v[64:67], v[48:63]
	ds_read_b128 v[238:241], v188 offset:20480
	s_waitcnt lgkmcnt(4)
	v_mfma_f32_32x32x16_bf16 v[32:47], v[242:245], v[64:67], v[32:47]
	ds_read_b128 v[242:245], v188 offset:24576
	s_waitcnt lgkmcnt(4)
	v_mfma_f32_32x32x16_bf16 v[16:31], v[246:249], v[64:67], v[16:31]
	ds_read_b128 v[246:249], v188 offset:28672
	s_waitcnt lgkmcnt(4)
	v_mfma_f32_32x32x16_bf16 v[0:15], v[230:233], v[64:67], v[0:15]
	ds_read_b128 v[230:233], v189 offset:16384
	v_cvt_pk_bf16_f32 v64, v80, v81
	v_cvt_pk_bf16_f32 v65, v82, v83
	v_cvt_pk_bf16_f32 v66, v84, v85
	v_cvt_pk_bf16_f32 v67, v86, v87
	s_waitcnt lgkmcnt(4)
	s_nop 0
	v_mfma_f32_32x32x16_bf16 v[48:63], v[234:237], v[64:67], v[48:63]
	ds_read_b128 v[234:237], v189 offset:20480
	s_waitcnt lgkmcnt(4)
	v_mfma_f32_32x32x16_bf16 v[32:47], v[238:241], v[64:67], v[32:47]
	ds_read_b128 v[238:241], v189 offset:24576
	s_waitcnt lgkmcnt(4)
	v_mfma_f32_32x32x16_bf16 v[16:31], v[242:245], v[64:67], v[16:31]
	ds_read_b128 v[242:245], v189 offset:28672
	s_waitcnt lgkmcnt(4)
	v_mfma_f32_32x32x16_bf16 v[0:15], v[246:249], v[64:67], v[0:15]
	v_cvt_pk_bf16_f32 v64, v69, v70
	v_cvt_pk_bf16_f32 v65, v71, v72
	v_cvt_pk_bf16_f32 v66, v73, v74
	v_cvt_pk_bf16_f32 v67, v75, v76
	s_waitcnt lgkmcnt(3)
	s_nop 0
	v_mfma_f32_32x32x16_bf16 v[48:63], v[230:233], v[64:67], v[48:63]
	s_waitcnt lgkmcnt(2)
	v_mfma_f32_32x32x16_bf16 v[32:47], v[234:237], v[64:67], v[32:47]
	s_waitcnt lgkmcnt(1)
	v_mfma_f32_32x32x16_bf16 v[16:31], v[238:241], v[64:67], v[16:31]
	s_waitcnt lgkmcnt(0)
	s_barrier
	v_mfma_f32_32x32x16_bf16 v[0:15], v[242:245], v[64:67], v[0:15]
	s_cbranch_scc1 .LBB0_712
	v_mov_b32_e32 v190, v68
	v_mov_b32_e32 v172, v191
	s_branch .LBB0_708

	.amdhsa_kernel _Z11mega_kernel6Params
		.amdhsa_group_segment_fixed_size 81920
		.amdhsa_private_segment_fixed_size 0
		.amdhsa_kernarg_size 592
		.amdhsa_user_sgpr_count 2
		.amdhsa_user_sgpr_dispatch_ptr 0
		.amdhsa_user_sgpr_queue_ptr 0
		.amdhsa_user_sgpr_kernarg_segment_ptr 1
		.amdhsa_user_sgpr_dispatch_id 0
		.amdhsa_user_sgpr_kernarg_preload_length 0
		.amdhsa_user_sgpr_kernarg_preload_offset 0
		.amdhsa_user_sgpr_private_segment_size 0
		.amdhsa_uses_dynamic_stack 0
		.amdhsa_enable_private_segment 0
		.amdhsa_system_sgpr_workgroup_id_x 1
		.amdhsa_system_sgpr_workgroup_id_y 0
		.amdhsa_system_sgpr_workgroup_id_z 0
		.amdhsa_system_sgpr_workgroup_info 0
		.amdhsa_system_vgpr_workitem_id 2
		.amdhsa_next_free_vgpr 256
		.amdhsa_next_free_sgpr 98
		.amdhsa_accum_offset 256
		.amdhsa_reserve_vcc 1
		.amdhsa_float_round_mode_32 0
		.amdhsa_float_round_mode_16_64 0
		.amdhsa_float_denorm_mode_32 3
		.amdhsa_float_denorm_mode_16_64 3
		.amdhsa_dx10_clamp 1
		.amdhsa_ieee_mode 1
		.amdhsa_fp16_overflow 0
		.amdhsa_tg_split 0
		.amdhsa_exception_fp_ieee_invalid_op 0
		.amdhsa_exception_fp_denorm_src 0
		.amdhsa_exception_fp_ieee_div_zero 0
		.amdhsa_exception_fp_ieee_overflow 0
		.amdhsa_exception_fp_ieee_underflow 0
		.amdhsa_exception_fp_ieee_inexact 0
		.amdhsa_exception_int_div_zero 0
	.end_amdhsa_kernel

amdhsa.kernels:
  - .agpr_count:     0
    .args:
      - .offset:         0
        .size:           336
        .value_kind:     by_value
      - .offset:         336
        .size:           4
        .value_kind:     hidden_block_count_x
      - .offset:         340
        .size:           4
        .value_kind:     hidden_block_count_y
      - .offset:         344
        .size:           4
        .value_kind:     hidden_block_count_z
      - .offset:         348
        .size:           2
        .value_kind:     hidden_group_size_x
      - .offset:         350
        .size:           2
        .value_kind:     hidden_group_size_y
      - .offset:         352
        .size:           2
        .value_kind:     hidden_group_size_z
      - .offset:         354
        .size:           2
        .value_kind:     hidden_remainder_x
      - .offset:         356
        .size:           2
        .value_kind:     hidden_remainder_y
      - .offset:         358
        .size:           2
        .value_kind:     hidden_remainder_z
      - .offset:         376
        .size:           8
        .value_kind:     hidden_global_offset_x
      - .offset:         384
        .size:           8
        .value_kind:     hidden_global_offset_y
      - .offset:         392
        .size:           8
        .value_kind:     hidden_global_offset_z
      - .offset:         400
        .size:           2
        .value_kind:     hidden_grid_dims
      - .offset:         424
        .size:           8
        .value_kind:     hidden_multigrid_sync_arg
    .group_segment_fixed_size: 81920
    .kernarg_segment_align: 8
    .kernarg_segment_size: 592
    .language:       OpenCL C
    .language_version:
      - 2
      - 0
    .max_flat_workgroup_size: 256
    .name:           _Z11mega_kernel6Params
    .private_segment_fixed_size: 0
    .sgpr_count:     104
    .sgpr_spill_count: 226
    .symbol:         _Z11mega_kernel6Params.kd
    .uniform_work_group_size: 1
    .uses_dynamic_stack: false
    .vgpr_count:     256
    .vgpr_spill_count: 0
    .wavefront_size: 64
